# stack7 + FFN-in row-statistics prologue with coalesced loads (8 lanes per row) and an in-register transpose-reduce over DPP
# speedup vs baseline: 1.0224x; 1.0159x over previous
; #define PG8_STAGE(bufoff, gbase, voff) do { _Pragma("unroll") for (int _i = 0; _i < 2; ++_i) \
;         __builtin_amdgcn_global_load_lds((const unsigned*)((const char*)(gbase) + (voff)[_i]), (LAS unsigned*)(lds + (bufoff) + ldsw + _i * 8192), 16, 0, 0); } while (0)
; #define PG8_LDA(dst, b, h) do { _Pragma("unroll") for (int m = 0; m < 4; ++m) _Pragma("unroll") for (int k = 0; k < 2; ++k) dst[m][k] = *(const LAS bf16x8*)(lds + PG8_SA(b, h) + aoff + m * 2048 + k * 1024); } while (0)
; #define PG8_LDB(dst, b, h) do { _Pragma("unroll") for (int n = 0; n < 2; ++n) _Pragma("unroll") for (int k = 0; k < 2; ++k) dst[n][k] = *(const LAS bf16x8*)(lds + PG8_SB(b, h) + boff + n * 2048 + k * 1024); } while (0)
; #define PG8_MMA(ai, bj, At, Bt) do { __builtin_amdgcn_s_setprio(1); _Pragma("unroll") for (int m = 0; m < 4; ++m) _Pragma("unroll") for (int n = 0; n < 2; ++n) _Pragma("unroll") for (int k = 0; k < 2; ++k) \
;         acc[ai][bj][m][n] = __builtin_amdgcn_mfma_f32_16x16x32_bf16(Bt[n][k], At[m][k], acc[ai][bj][m][n], 0, 0, 0); __builtin_amdgcn_s_setprio(0); } while (0)
; #define PG8_WAIT_V(n) asm volatile("s_waitcnt vmcnt(" #n ")" ::: "memory")
; #define PG8_WAIT_L(n) asm volatile("s_waitcnt lgkmcnt(" #n ")" ::: "memory")
; #define PG8_BAR __builtin_amdgcn_s_barrier()
; #define PG8_SCHED __builtin_amdgcn_sched_barrier(0)
; template <class Epi>
; __device__ __forceinline__ void gemm_phase(LAS unsigned char* lds, const Gemm g, const StaticOrder& S, const Epi& E) {
;     ...
;             PG8_LDB(B0, 0, 0); PG8_SCHED; PG8_LDA(At, 0, 0); PG8_STAGE(PG8_SA(1, 1), a1 + hstep, voffA);
;             PG8_WAIT_L(8); PG8_BAR; PG8_WAIT_L(0); PG8_MMA(0, 0, At, B0); PG8_BAR; PG8_SCHED;
;             PG8_LDB(B1, 0, 1); PG8_STAGE(PG8_SB(0, 0), b2, voffB);
;             PG8_BAR; PG8_WAIT_L(0); PG8_MMA(0, 1, At, B1); PG8_BAR;
;             PG8_LDA(At, 0, 1); PG8_STAGE(PG8_SA(0, 0), a2, voffA);
;             PG8_BAR; PG8_WAIT_L(0); PG8_MMA(1, 0, At, B0); PG8_BAR; PG8_SCHED;
;             PG8_STAGE(PG8_SB(0, 1), b2 + hstep, voffB);
;             PG8_WAIT_V(6); PG8_BAR; PG8_MMA(1, 1, At, B1); PG8_BAR;
.LBB0_878:
	s_add_u32 s14, s10, 0xfffc0080
	s_addc_u32 s15, s11, -1
	s_add_i32 s60, 0, 0x10000
	v_add_u32_e32 v76, s60, v217
	ds_read_b128 v[60:63], v76
	ds_read_b128 v[64:67], v76 offset:1024
	ds_read_b128 v[72:75], v76 offset:2048
	ds_read_b128 v[76:79], v76 offset:3072
	s_cmp_eq_u32 s59, 12
	s_cselect_b32 s17, s39, s15
	s_cselect_b32 s16, s55, s14
	s_cselect_b32 s15, s1, s58
	s_cselect_b32 s14, s56, s57
	v_lshl_add_u64 v[188:189], s[10:11], 0, v[174:175]
	s_add_i32 m0, s26, 0xc000
	ds_read_b128 v[80:83], v223
	ds_read_b128 v[84:87], v223 offset:1024
	ds_read_b128 v[92:95], v223 offset:2048
	ds_read_b128 v[96:99], v223 offset:3072
	ds_read_b128 v[160:163], v223 offset:4096
	ds_read_b128 v[164:167], v223 offset:5120
	ds_read_b128 v[178:181], v223 offset:6144
	ds_read_b128 v[182:185], v223 offset:7168
	global_load_lds_dwordx4 v[188:189], off
	v_lshl_add_u64 v[188:189], s[10:11], 0, v[176:177]
	s_add_i32 m0, s26, 0xe000
	s_nop 0
	global_load_lds_dwordx4 v[188:189], off
	s_waitcnt lgkmcnt(8)
	s_barrier
	s_waitcnt lgkmcnt(0)
	s_setprio 1
	s_waitcnt lgkmcnt(0)
	v_mfma_f32_16x16x32_bf16 v[156:159], v[60:63], v[80:83], v[156:159]
	v_mfma_f32_16x16x32_bf16 v[148:151], v[72:75], v[80:83], v[148:151]
	v_mfma_f32_16x16x32_bf16 v[140:143], v[60:63], v[92:95], v[140:143]
	v_mfma_f32_16x16x32_bf16 v[132:135], v[72:75], v[92:95], v[132:135]
	v_mfma_f32_16x16x32_bf16 v[124:127], v[60:63], v[160:163], v[124:127]
	v_mfma_f32_16x16x32_bf16 v[116:119], v[72:75], v[160:163], v[116:119]
	v_mfma_f32_16x16x32_bf16 v[108:111], v[60:63], v[178:181], v[108:111]
	v_mfma_f32_16x16x32_bf16 v[100:103], v[72:75], v[178:181], v[100:103]
	v_mfma_f32_16x16x32_bf16 v[156:159], v[64:67], v[84:87], v[156:159]
	v_mfma_f32_16x16x32_bf16 v[148:151], v[76:79], v[84:87], v[148:151]
	v_mfma_f32_16x16x32_bf16 v[140:143], v[64:67], v[96:99], v[140:143]
	v_mfma_f32_16x16x32_bf16 v[132:135], v[76:79], v[96:99], v[132:135]
	v_mfma_f32_16x16x32_bf16 v[124:127], v[64:67], v[164:167], v[124:127]
	v_mfma_f32_16x16x32_bf16 v[116:119], v[76:79], v[164:167], v[116:119]
	v_mfma_f32_16x16x32_bf16 v[108:111], v[64:67], v[182:185], v[108:111]
	v_mfma_f32_16x16x32_bf16 v[100:103], v[76:79], v[182:185], v[100:103]
	s_setprio 0
	s_barrier
	s_add_i32 s62, 0, 0x14000
	s_add_i32 s60, s60, s21
	v_add_u32_e32 v186, s62, v217
	v_lshl_add_u64 v[188:189], s[14:15], 0, v[190:191]
	s_mov_b32 m0, s60
	ds_read_b128 v[194:197], v186
	ds_read_b128 v[198:201], v186 offset:1024
	ds_read_b128 v[204:207], v186 offset:2048
	ds_read_b128 v[208:211], v186 offset:3072
	global_load_lds_dwordx4 v[188:189], off
	v_lshl_add_u64 v[224:225], s[14:15], 0, v[168:169]
	s_add_i32 m0, s60, 0x2000
	s_nop 0
	global_load_lds_dwordx4 v[224:225], off
	s_barrier
	s_waitcnt lgkmcnt(0)
	s_setprio 1
	s_waitcnt lgkmcnt(0)
	v_mfma_f32_16x16x32_bf16 v[152:155], v[194:197], v[80:83], v[152:155]
	v_mfma_f32_16x16x32_bf16 v[80:83], v[204:207], v[80:83], v[144:147]
	v_mfma_f32_16x16x32_bf16 v[152:155], v[198:201], v[84:87], v[152:155]
	v_mfma_f32_16x16x32_bf16 v[80:83], v[208:211], v[84:87], v[80:83]
	v_mfma_f32_16x16x32_bf16 v[84:87], v[194:197], v[92:95], v[136:139]
	v_mfma_f32_16x16x32_bf16 v[92:95], v[204:207], v[92:95], v[128:131]
	v_mfma_f32_16x16x32_bf16 v[112:115], v[204:207], v[160:163], v[112:115]
	v_mfma_f32_16x16x32_bf16 v[104:107], v[194:197], v[178:181], v[104:107]
	v_mfma_f32_16x16x32_bf16 v[88:91], v[204:207], v[178:181], v[88:91]
	v_mfma_f32_16x16x32_bf16 v[84:87], v[198:201], v[96:99], v[84:87]
	v_mfma_f32_16x16x32_bf16 v[92:95], v[208:211], v[96:99], v[92:95]
	v_mfma_f32_16x16x32_bf16 v[96:99], v[194:197], v[160:163], v[120:123]
	v_mfma_f32_16x16x32_bf16 v[112:115], v[208:211], v[164:167], v[112:115]
	v_mfma_f32_16x16x32_bf16 v[104:107], v[198:201], v[182:185], v[104:107]
	v_mfma_f32_16x16x32_bf16 v[88:91], v[208:211], v[182:185], v[88:91]
	v_mfma_f32_16x16x32_bf16 v[96:99], v[198:201], v[164:167], v[96:99]
	s_setprio 0
	s_mov_b32 m0, s26
	v_lshl_add_u64 v[226:227], s[16:17], 0, v[172:173]
	s_barrier
	ds_read_b128 v[120:123], v223 offset:16384
	ds_read_b128 v[128:131], v223 offset:17408
	ds_read_b128 v[136:139], v223 offset:18432
	ds_read_b128 v[144:147], v223 offset:19456
	ds_read_b128 v[160:163], v223 offset:20480
	ds_read_b128 v[164:167], v223 offset:21504
	ds_read_b128 v[178:181], v223 offset:22528
	ds_read_b128 v[182:185], v223 offset:23552
	global_load_lds_dwordx4 v[226:227], off
	v_lshl_add_u64 v[240:241], s[16:17], 0, v[170:171]
	s_mov_b32 m0, s27
	s_nop 0
	global_load_lds_dwordx4 v[240:241], off
	s_barrier
	s_waitcnt lgkmcnt(0)
	s_setprio 1
	s_waitcnt lgkmcnt(0)
	v_mfma_f32_16x16x32_bf16 v[68:71], v[60:63], v[120:123], v[68:71]
	v_mfma_f32_16x16x32_bf16 v[52:55], v[72:75], v[120:123], v[52:55]
	v_mfma_f32_16x16x32_bf16 v[44:47], v[60:63], v[136:139], v[44:47]
	v_mfma_f32_16x16x32_bf16 v[36:39], v[72:75], v[136:139], v[36:39]
	v_mfma_f32_16x16x32_bf16 v[28:31], v[60:63], v[160:163], v[28:31]
	v_mfma_f32_16x16x32_bf16 v[20:23], v[72:75], v[160:163], v[20:23]
	v_mfma_f32_16x16x32_bf16 v[12:15], v[60:63], v[178:181], v[12:15]
	v_mfma_f32_16x16x32_bf16 v[4:7], v[72:75], v[178:181], v[4:7]
	v_mfma_f32_16x16x32_bf16 v[68:71], v[64:67], v[128:131], v[68:71]
	v_mfma_f32_16x16x32_bf16 v[52:55], v[76:79], v[128:131], v[52:55]
	v_mfma_f32_16x16x32_bf16 v[44:47], v[64:67], v[144:147], v[44:47]
	v_mfma_f32_16x16x32_bf16 v[36:39], v[76:79], v[144:147], v[36:39]
	v_mfma_f32_16x16x32_bf16 v[28:31], v[64:67], v[164:167], v[28:31]
	v_mfma_f32_16x16x32_bf16 v[20:23], v[76:79], v[164:167], v[20:23]
	v_mfma_f32_16x16x32_bf16 v[12:15], v[64:67], v[182:185], v[12:15]
	v_mfma_f32_16x16x32_bf16 v[4:7], v[76:79], v[182:185], v[4:7]
	s_setprio 0
	s_barrier
; #define PG8_STAGE(bufoff, gbase, voff) do { _Pragma("unroll") for (int _i = 0; _i < 2; ++_i) \
;         __builtin_amdgcn_global_load_lds((const unsigned*)((const char*)(gbase) + (voff)[_i]), (LAS unsigned*)(lds + (bufoff) + ldsw + _i * 8192), 16, 0, 0); } while (0)
; #define PG8_LDA(dst, b, h) do { _Pragma("unroll") for (int m = 0; m < 4; ++m) _Pragma("unroll") for (int k = 0; k < 2; ++k) dst[m][k] = *(const LAS bf16x8*)(lds + PG8_SA(b, h) + aoff + m * 2048 + k * 1024); } while (0)
; #define PG8_LDB(dst, b, h) do { _Pragma("unroll") for (int n = 0; n < 2; ++n) _Pragma("unroll") for (int k = 0; k < 2; ++k) dst[n][k] = *(const LAS bf16x8*)(lds + PG8_SB(b, h) + boff + n * 2048 + k * 1024); } while (0)
; #define PG8_MMA(ai, bj, At, Bt) do { __builtin_amdgcn_s_setprio(1); _Pragma("unroll") for (int m = 0; m < 4; ++m) _Pragma("unroll") for (int n = 0; n < 2; ++n) _Pragma("unroll") for (int k = 0; k < 2; ++k) \
;         acc[ai][bj][m][n] = __builtin_amdgcn_mfma_f32_16x16x32_bf16(Bt[n][k], At[m][k], acc[ai][bj][m][n], 0, 0, 0); __builtin_amdgcn_s_setprio(0); } while (0)
; #define PG8_WAIT_V(n) asm volatile("s_waitcnt vmcnt(" #n ")" ::: "memory")
; #define PG8_WAIT_L(n) asm volatile("s_waitcnt lgkmcnt(" #n ")" ::: "memory")
; #define PG8_BAR __builtin_amdgcn_s_barrier()
; #define PG8_SCHED __builtin_amdgcn_sched_barrier(0)
; template <class Epi>
; __device__ __forceinline__ void gemm_phase(LAS unsigned char* lds, const Gemm g, const StaticOrder& S, const Epi& E) {
;     ...
;             PG8_STAGE(PG8_SB(0, 1), b2 + hstep, voffB);
;             PG8_WAIT_V(6); PG8_BAR; PG8_MMA(1, 1, At, B1); PG8_BAR;
;             PG8_LDB(B0, 1, 0); PG8_SCHED; PG8_LDA(At, 1, 0); PG8_STAGE(PG8_SA(0, 1), a2 + hstep, voffA);
;             PG8_WAIT_L(8); PG8_BAR; PG8_WAIT_L(0); PG8_MMA(0, 0, At, B0); PG8_BAR; PG8_SCHED;
;             PG8_LDB(B1, 1, 1); PG8_STAGE(PG8_SB(1, 0), b3, voffB);
;             PG8_BAR; PG8_WAIT_L(0); PG8_MMA(0, 1, At, B1); PG8_BAR;
;             PG8_LDA(At, 1, 1); PG8_STAGE(PG8_SA(1, 0), a3, voffA);
;             PG8_BAR; PG8_WAIT_L(0); PG8_MMA(1, 0, At, B0); PG8_BAR; PG8_SCHED;
	s_add_u32 s60, s14, 0x40000
	s_addc_u32 s61, s15, 0
	s_add_i32 s62, s62, s21
	v_lshl_add_u64 v[60:61], s[60:61], 0, v[190:191]
	s_mov_b32 m0, s62
	s_nop 0
	global_load_lds_dwordx4 v[60:61], off
	v_lshl_add_u64 v[60:61], s[60:61], 0, v[168:169]
	s_add_i32 m0, s62, 0x2000
	s_nop 0
	global_load_lds_dwordx4 v[60:61], off
	s_waitcnt vmcnt(6)
	s_barrier
	s_setprio 1
	v_mfma_f32_16x16x32_bf16 v[56:59], v[194:197], v[120:123], v[56:59]
	v_mfma_f32_16x16x32_bf16 v[48:51], v[204:207], v[120:123], v[48:51]
	v_mfma_f32_16x16x32_bf16 v[40:43], v[194:197], v[136:139], v[40:43]
	v_mfma_f32_16x16x32_bf16 v[32:35], v[204:207], v[136:139], v[32:35]
	v_mfma_f32_16x16x32_bf16 v[24:27], v[194:197], v[160:163], v[24:27]
	v_mfma_f32_16x16x32_bf16 v[16:19], v[204:207], v[160:163], v[16:19]
	v_mfma_f32_16x16x32_bf16 v[8:11], v[194:197], v[178:181], v[8:11]
	v_mfma_f32_16x16x32_bf16 v[0:3], v[204:207], v[178:181], v[0:3]
	v_mfma_f32_16x16x32_bf16 v[56:59], v[198:201], v[128:131], v[56:59]
	v_mfma_f32_16x16x32_bf16 v[48:51], v[208:211], v[128:131], v[48:51]
	v_mfma_f32_16x16x32_bf16 v[40:43], v[198:201], v[144:147], v[40:43]
	v_mfma_f32_16x16x32_bf16 v[32:35], v[208:211], v[144:147], v[32:35]
	v_mfma_f32_16x16x32_bf16 v[24:27], v[198:201], v[164:167], v[24:27]
	v_mfma_f32_16x16x32_bf16 v[16:19], v[208:211], v[164:167], v[16:19]
	v_mfma_f32_16x16x32_bf16 v[8:11], v[198:201], v[182:185], v[8:11]
	v_mfma_f32_16x16x32_bf16 v[0:3], v[208:211], v[182:185], v[0:3]
	s_setprio 0
	s_add_i32 s60, 0, 0x18000
	v_add_u32_e32 v76, s60, v217
	s_barrier
	ds_read_b128 v[60:63], v76
	ds_read_b128 v[64:67], v76 offset:1024
	ds_read_b128 v[72:75], v76 offset:2048
	ds_read_b128 v[76:79], v76 offset:3072
	s_add_u32 s16, s16, 0x40000
	s_addc_u32 s17, s17, 0
	s_mov_b32 m0, s30
	v_lshl_add_u64 v[136:137], s[16:17], 0, v[172:173]
	ds_read_b128 v[120:123], v223 offset:32768
	ds_read_b128 v[128:131], v223 offset:33792
	ds_read_b128 v[160:163], v223 offset:34816
	ds_read_b128 v[164:167], v223 offset:35840
	ds_read_b128 v[178:181], v223 offset:36864
	ds_read_b128 v[182:185], v223 offset:37888
	ds_read_b128 v[194:197], v223 offset:38912
	ds_read_b128 v[198:201], v223 offset:39936
	global_load_lds_dwordx4 v[136:137], off
	v_lshl_add_u64 v[136:137], s[16:17], 0, v[170:171]
	s_mov_b32 m0, s31
	s_nop 0
	global_load_lds_dwordx4 v[136:137], off
	s_waitcnt lgkmcnt(8)
	s_barrier
	s_waitcnt lgkmcnt(0)
	s_setprio 1
	s_waitcnt lgkmcnt(0)
	v_mfma_f32_16x16x32_bf16 v[136:139], v[60:63], v[120:123], v[156:159]
	v_mfma_f32_16x16x32_bf16 v[156:159], v[64:67], v[128:131], v[136:139]
	v_mfma_f32_16x16x32_bf16 v[136:139], v[72:75], v[120:123], v[148:151]
	v_mfma_f32_16x16x32_bf16 v[148:151], v[76:79], v[128:131], v[136:139]
	v_mfma_f32_16x16x32_bf16 v[136:139], v[60:63], v[160:163], v[140:143]
	v_mfma_f32_16x16x32_bf16 v[132:135], v[72:75], v[160:163], v[132:135]
	v_mfma_f32_16x16x32_bf16 v[124:127], v[60:63], v[178:181], v[124:127]
	v_mfma_f32_16x16x32_bf16 v[116:119], v[72:75], v[178:181], v[116:119]
	v_mfma_f32_16x16x32_bf16 v[108:111], v[60:63], v[194:197], v[108:111]
	v_mfma_f32_16x16x32_bf16 v[100:103], v[72:75], v[194:197], v[100:103]
	v_mfma_f32_16x16x32_bf16 v[140:143], v[64:67], v[164:167], v[136:139]
	v_mfma_f32_16x16x32_bf16 v[132:135], v[76:79], v[164:167], v[132:135]
	v_mfma_f32_16x16x32_bf16 v[124:127], v[64:67], v[182:185], v[124:127]
	v_mfma_f32_16x16x32_bf16 v[116:119], v[76:79], v[182:185], v[116:119]
	v_mfma_f32_16x16x32_bf16 v[108:111], v[64:67], v[198:201], v[108:111]
	v_mfma_f32_16x16x32_bf16 v[100:103], v[76:79], v[198:201], v[100:103]
	s_setprio 0
	s_barrier
	s_add_i32 s16, 0, 0x1c000
	v_add_u32_e32 v136, s16, v217
	s_add_i32 s17, s60, s21
	ds_read_b128 v[204:207], v136
	ds_read_b128 v[208:211], v136 offset:1024
	ds_read_b128 v[212:215], v136 offset:2048
	ds_read_b128 v[218:221], v136 offset:3072
	v_lshl_add_u64 v[136:137], v[188:189], 0, s[28:29]
	s_mov_b32 m0, s17
	s_nop 0
	global_load_lds_dwordx4 v[136:137], off
	v_lshl_add_u64 v[136:137], v[224:225], 0, s[28:29]
	s_add_i32 m0, s17, 0x2000
	s_nop 0
	global_load_lds_dwordx4 v[136:137], off
	s_barrier
	s_waitcnt lgkmcnt(0)
	s_setprio 1
	s_waitcnt lgkmcnt(0)
	v_mfma_f32_16x16x32_bf16 v[80:83], v[212:215], v[120:123], v[80:83]
	v_mfma_f32_16x16x32_bf16 v[136:139], v[204:207], v[120:123], v[152:155]
	v_mfma_f32_16x16x32_bf16 v[144:147], v[218:221], v[128:131], v[80:83]
	v_mfma_f32_16x16x32_bf16 v[80:83], v[204:207], v[160:163], v[84:87]
	v_mfma_f32_16x16x32_bf16 v[152:155], v[208:211], v[128:131], v[136:139]
	v_mfma_f32_16x16x32_bf16 v[136:139], v[208:211], v[164:167], v[80:83]
	v_mfma_f32_16x16x32_bf16 v[80:83], v[212:215], v[160:163], v[92:95]
	v_mfma_f32_16x16x32_bf16 v[128:131], v[218:221], v[164:167], v[80:83]
	v_mfma_f32_16x16x32_bf16 v[80:83], v[204:207], v[178:181], v[96:99]
	v_mfma_f32_16x16x32_bf16 v[120:123], v[208:211], v[182:185], v[80:83]
	v_mfma_f32_16x16x32_bf16 v[80:83], v[212:215], v[178:181], v[112:115]
	v_mfma_f32_16x16x32_bf16 v[112:115], v[218:221], v[182:185], v[80:83]
	v_mfma_f32_16x16x32_bf16 v[80:83], v[204:207], v[194:197], v[104:107]
	v_mfma_f32_16x16x32_bf16 v[104:107], v[208:211], v[198:201], v[80:83]
	v_mfma_f32_16x16x32_bf16 v[80:83], v[212:215], v[194:197], v[88:91]
	v_mfma_f32_16x16x32_bf16 v[88:91], v[218:221], v[198:201], v[80:83]
	s_setprio 0
	s_mov_b32 m0, s51
	v_lshl_add_u64 v[188:189], v[226:227], 0, s[28:29]
	s_barrier
	s_nop 2
	ds_read_b128 v[80:83], v223 offset:49152
	ds_read_b128 v[84:87], v223 offset:50176
	ds_read_b128 v[92:95], v223 offset:51200
	ds_read_b128 v[96:99], v223 offset:52224
	ds_read_b128 v[160:163], v223 offset:53248
	ds_read_b128 v[164:167], v223 offset:54272
	ds_read_b128 v[178:181], v223 offset:55296
	ds_read_b128 v[182:185], v223 offset:56320
	global_load_lds_dwordx4 v[188:189], off
	v_lshl_add_u64 v[188:189], v[240:241], 0, s[28:29]
	s_mov_b32 m0, s52
	s_nop 0
	global_load_lds_dwordx4 v[188:189], off
	s_barrier
; #define PG8_STAGE(bufoff, gbase, voff) do { _Pragma("unroll") for (int _i = 0; _i < 2; ++_i) \
;         __builtin_amdgcn_global_load_lds((const unsigned*)((const char*)(gbase) + (voff)[_i]), (LAS unsigned*)(lds + (bufoff) + ldsw + _i * 8192), 16, 0, 0); } while (0)
; #define PG8_LDA(dst, b, h) do { _Pragma("unroll") for (int m = 0; m < 4; ++m) _Pragma("unroll") for (int k = 0; k < 2; ++k) dst[m][k] = *(const LAS bf16x8*)(lds + PG8_SA(b, h) + aoff + m * 2048 + k * 1024); } while (0)
; #define PG8_LDB(dst, b, h) do { _Pragma("unroll") for (int n = 0; n < 2; ++n) _Pragma("unroll") for (int k = 0; k < 2; ++k) dst[n][k] = *(const LAS bf16x8*)(lds + PG8_SB(b, h) + boff + n * 2048 + k * 1024); } while (0)
; #define PG8_MMA(ai, bj, At, Bt) do { __builtin_amdgcn_s_setprio(1); _Pragma("unroll") for (int m = 0; m < 4; ++m) _Pragma("unroll") for (int n = 0; n < 2; ++n) _Pragma("unroll") for (int k = 0; k < 2; ++k) \
;         acc[ai][bj][m][n] = __builtin_amdgcn_mfma_f32_16x16x32_bf16(Bt[n][k], At[m][k], acc[ai][bj][m][n], 0, 0, 0); __builtin_amdgcn_s_setprio(0); } while (0)
; #define PG8_WAIT_V(n) asm volatile("s_waitcnt vmcnt(" #n ")" ::: "memory")
; #define PG8_WAIT_L(n) asm volatile("s_waitcnt lgkmcnt(" #n ")" ::: "memory")
; __device__ __forceinline__ void row_stats(const float* st, int row, int fq, float& mu, float& rs) {
;     const f32x4 a = *(const f32x4*)(st + (size_t)row * 32 + fq * 8), b = *(const f32x4*)(st + (size_t)row * 32 + fq * 8 + 4);
;     float s = (a[0] + a[2]) + (b[0] + b[2]), q = (a[1] + a[3]) + (b[1] + b[3]);
;     s += __shfl_xor(s, 16); s += __shfl_xor(s, 32); q += __shfl_xor(q, 16); q += __shfl_xor(q, 32);
; template <class Epi>
; __device__ __forceinline__ void gemm_phase(LAS unsigned char* lds, const Gemm g, const StaticOrder& S, const Epi& E) {
;     ...
;             PG8_WAIT_L(8); PG8_BAR; PG8_WAIT_L(0); PG8_MMA(0, 0, At, B0); PG8_BAR; PG8_SCHED;
;             PG8_LDB(B1, 1, 1); PG8_STAGE(PG8_SB(1, 0), b3, voffB);
;             PG8_BAR; PG8_WAIT_L(0); PG8_MMA(0, 1, At, B1); PG8_BAR;
;             PG8_LDA(At, 1, 1); PG8_STAGE(PG8_SA(1, 0), a3, voffA);
;             PG8_BAR; PG8_WAIT_L(0); PG8_MMA(1, 0, At, B0); PG8_BAR; PG8_SCHED;
;             PG8_STAGE(PG8_SB(1, 1), b3 + hstep, voffB);
;             PG8_WAIT_V(6); PG8_BAR; PG8_MMA(1, 1, At, B1); PG8_BAR;
;         }
;         E(acc, cur, wr, wc, fr, fq);
	s_waitcnt lgkmcnt(0)
	s_setprio 1
	s_waitcnt lgkmcnt(0)
	v_mfma_f32_16x16x32_bf16 v[68:71], v[60:63], v[80:83], v[68:71]
	v_mfma_f32_16x16x32_bf16 v[52:55], v[72:75], v[80:83], v[52:55]
	v_mfma_f32_16x16x32_bf16 v[44:47], v[60:63], v[92:95], v[44:47]
	v_mfma_f32_16x16x32_bf16 v[36:39], v[72:75], v[92:95], v[36:39]
	v_mfma_f32_16x16x32_bf16 v[28:31], v[60:63], v[160:163], v[28:31]
	v_mfma_f32_16x16x32_bf16 v[20:23], v[72:75], v[160:163], v[20:23]
	v_mfma_f32_16x16x32_bf16 v[12:15], v[60:63], v[178:181], v[12:15]
	v_mfma_f32_16x16x32_bf16 v[4:7], v[72:75], v[178:181], v[4:7]
	v_mfma_f32_16x16x32_bf16 v[68:71], v[64:67], v[84:87], v[68:71]
	v_mfma_f32_16x16x32_bf16 v[52:55], v[76:79], v[84:87], v[52:55]
	v_mfma_f32_16x16x32_bf16 v[44:47], v[64:67], v[96:99], v[44:47]
	v_mfma_f32_16x16x32_bf16 v[36:39], v[76:79], v[96:99], v[36:39]
	v_mfma_f32_16x16x32_bf16 v[28:31], v[64:67], v[164:167], v[28:31]
	v_mfma_f32_16x16x32_bf16 v[20:23], v[76:79], v[164:167], v[20:23]
	v_mfma_f32_16x16x32_bf16 v[12:15], v[64:67], v[182:185], v[12:15]
	v_mfma_f32_16x16x32_bf16 v[4:7], v[76:79], v[182:185], v[4:7]
	s_setprio 0
	s_barrier
	s_add_u32 s14, s14, 0x40080
	s_addc_u32 s15, s15, 0
	s_add_i32 s16, s16, s21
	v_lshl_add_u64 v[60:61], s[14:15], 0, v[190:191]
	s_mov_b32 m0, s16
	s_nop 0
	global_load_lds_dwordx4 v[60:61], off
	v_lshl_add_u64 v[60:61], s[14:15], 0, v[168:169]
	s_add_i32 m0, s16, 0x2000
	s_nop 0
	global_load_lds_dwordx4 v[60:61], off
	s_waitcnt vmcnt(6)
	s_barrier
	s_setprio 1
	v_mfma_f32_16x16x32_bf16 v[56:59], v[204:207], v[80:83], v[56:59]
	v_mfma_f32_16x16x32_bf16 v[48:51], v[212:215], v[80:83], v[48:51]
	v_mfma_f32_16x16x32_bf16 v[40:43], v[204:207], v[92:95], v[40:43]
	v_mfma_f32_16x16x32_bf16 v[32:35], v[212:215], v[92:95], v[32:35]
	v_mfma_f32_16x16x32_bf16 v[24:27], v[204:207], v[160:163], v[24:27]
	v_mfma_f32_16x16x32_bf16 v[16:19], v[212:215], v[160:163], v[16:19]
	v_mfma_f32_16x16x32_bf16 v[8:11], v[204:207], v[178:181], v[8:11]
	v_mfma_f32_16x16x32_bf16 v[0:3], v[212:215], v[178:181], v[0:3]
	v_mfma_f32_16x16x32_bf16 v[56:59], v[208:211], v[84:87], v[56:59]
	v_mfma_f32_16x16x32_bf16 v[48:51], v[218:221], v[84:87], v[48:51]
	v_mfma_f32_16x16x32_bf16 v[40:43], v[208:211], v[96:99], v[40:43]
	v_mfma_f32_16x16x32_bf16 v[32:35], v[218:221], v[96:99], v[32:35]
	v_mfma_f32_16x16x32_bf16 v[24:27], v[208:211], v[164:167], v[24:27]
	v_mfma_f32_16x16x32_bf16 v[16:19], v[218:221], v[164:167], v[16:19]
	v_mfma_f32_16x16x32_bf16 v[8:11], v[208:211], v[182:185], v[8:11]
	v_mfma_f32_16x16x32_bf16 v[0:3], v[218:221], v[182:185], v[0:3]
	s_setprio 0
	s_add_i32 s59, s59, 2
	s_add_u32 s10, s10, 0x100
	s_addc_u32 s11, s11, 0
	s_add_u32 s57, s57, 0x100
	s_addc_u32 s58, s58, 0
	s_cmp_gt_u32 s59, 13
	s_barrier
	s_cbranch_scc0 .LBB0_878
	s_lshl_b32 s10, s54, 8
	s_ashr_i32 s11, s10, 31
	s_lshl_b64 s[10:11], s[10:11], 2
	s_add_u32 s14, s2, s10
	s_addc_u32 s15, s46, s11
	v_xor_b32_e32 v162, 16, v231
	s_add_u32 s10, s47, s10
	v_cmp_lt_i32_e32 vcc, v162, v232
	v_mov_b32_e32 v161, v187
	v_mov_b32_e32 v60, v203
	s_addc_u32 s11, s48, s11
	s_lshl_b32 s1, s5, 8
	v_cndmask_b32_e32 v162, v231, v162, vcc
	s_add_i32 s1, s1, s49
	v_lshlrev_b32_e32 v160, 3, v60
	v_lshlrev_b32_e32 v239, 2, v162
	v_xor_b32_e32 v162, 32, v231
	v_add_u32_e32 v188, s50, v160
	v_add_u32_e32 v210, s1, v161
	v_readlane_b32 s4, v253, 21
	v_cmp_lt_i32_e32 vcc, v162, v232
	v_ashrrev_i32_e32 v189, 31, v188
	v_ashrrev_i32_e32 v161, 31, v160
	v_readlane_b32 s5, v253, 22
	v_cndmask_b32_e32 v162, v231, v162, vcc
	v_ashrrev_i32_e32 v211, 31, v210
	v_lshlrev_b64 v[60:61], 2, v[188:189]
	v_lshl_add_u64 v[160:161], v[160:161], 2, s[4:5]
	v_lshlrev_b32_e32 v225, 2, v162
	v_lshlrev_b64 v[162:163], 7, v[210:211]
	v_lshl_add_u64 v[64:65], s[14:15], 0, v[60:61]
	v_lshl_add_u64 v[84:85], s[10:11], 0, v[60:61]
	v_lshl_add_u64 v[166:167], v[160:161], 0, v[162:163]
	v_and_b32_e32 v194, 15, v231
	v_lshrrev_b32_e32 v195, 4, v231
	v_lshrrev_b32_e32 v196, 3, v194
	v_and_b32_e32 v197, 7, v194
	v_lshl_add_u32 v196, v195, 1, v196
	v_sub_u32_e32 v196, v196, v194
	v_lshlrev_b32_e32 v196, 7, v196
	v_lshl_add_u32 v196, v197, 4, v196
	v_lshlrev_b32_e32 v195, 5, v195
	v_sub_u32_e32 v196, v196, v195
	v_ashrrev_i32_e32 v197, 31, v196
	v_and_b32_e32 v194, 1, v231
	v_cmp_ne_u32_e64 s[98:99], 0, v194
	v_and_b32_e32 v194, 2, v231
	v_cmp_ne_u32_e64 s[100:101], 0, v194
	v_lshl_add_u64 v[196:197], v[166:167], 0, v[196:197]
	v_mov_b32_e32 v195, 0
	v_add_co_u32_e32 v212, vcc, 0x1000, v196
	s_nop 1
	v_addc_co_u32_e32 v213, vcc, 0, v197, vcc
	global_load_dwordx4 v[60:63], v[196:197], off
	global_load_dwordx4 v[72:75], v[196:197], off offset:1024
	global_load_dwordx4 v[76:79], v[196:197], off offset:2048
	global_load_dwordx4 v[80:83], v[196:197], off offset:3072
	global_load_dwordx4 v[92:95], v[212:213], off
	global_load_dwordx4 v[96:99], v[212:213], off offset:1024
	global_load_dwordx4 v[204:207], v[212:213], off offset:2048
	global_load_dwordx4 v[178:181], v[212:213], off offset:3072
	s_waitcnt vmcnt(0)
; __device__ __forceinline__ void row_stats(const float* st, int row, int fq, float& mu, float& rs) {
;     const f32x4 a = *(const f32x4*)(st + (size_t)row * 32 + fq * 8), b = *(const f32x4*)(st + (size_t)row * 32 + fq * 8 + 4);
;     float s = (a[0] + a[2]) + (b[0] + b[2]), q = (a[1] + a[3]) + (b[1] + b[3]);
;     s += __shfl_xor(s, 16); s += __shfl_xor(s, 32); q += __shfl_xor(q, 16); q += __shfl_xor(q, 32);
;     mu = s * (1.0f / 1024.0f); const float var = fmaxf(q * (1.0f / 1024.0f) - mu * mu, 0.f); rs = rsqrtf(var + LN_EPS);
;     __device__ __forceinline__ void operator()(const f32x4 (&acc)[2][2][4][2], const Unit& u, int wr, int wc, int fr_, int fq_) const {
;     ...
;         for (int q = 0; q < 8; ++q) row_stats(st1, u.pm * 256 + (q >> 2) * 128 + (q & 3) * 16 + wr * 64 + fr, fq, mus[q], rss[q]);
	v_pk_add_f32 v[60:61], v[60:61], v[62:63]
	v_pk_add_f32 v[72:73], v[72:73], v[74:75]
	v_pk_add_f32 v[76:77], v[76:77], v[78:79]
	v_pk_add_f32 v[80:81], v[80:81], v[82:83]
	v_pk_add_f32 v[92:93], v[92:93], v[94:95]
	v_pk_add_f32 v[96:97], v[96:97], v[98:99]
	v_pk_add_f32 v[204:205], v[204:205], v[206:207]
	v_pk_add_f32 v[178:179], v[178:179], v[180:181]
	v_cndmask_b32_e64 v208, v72, v60, s[98:99]
	v_cndmask_b32_e64 v209, v73, v61, s[98:99]
	v_cndmask_b32_e64 v60, v60, v72, s[98:99]
	v_cndmask_b32_e64 v61, v61, v73, s[98:99]
	v_mov_b32_dpp v72, v208 quad_perm:[1,0,3,2] row_mask:0xf bank_mask:0xf
	v_mov_b32_dpp v73, v209 quad_perm:[1,0,3,2] row_mask:0xf bank_mask:0xf
	v_pk_add_f32 v[60:61], v[60:61], v[72:73]
	v_cndmask_b32_e64 v208, v80, v76, s[98:99]
	v_cndmask_b32_e64 v209, v81, v77, s[98:99]
	v_cndmask_b32_e64 v76, v76, v80, s[98:99]
	v_cndmask_b32_e64 v77, v77, v81, s[98:99]
	v_mov_b32_dpp v80, v208 quad_perm:[1,0,3,2] row_mask:0xf bank_mask:0xf
	v_mov_b32_dpp v81, v209 quad_perm:[1,0,3,2] row_mask:0xf bank_mask:0xf
	v_pk_add_f32 v[76:77], v[76:77], v[80:81]
	v_cndmask_b32_e64 v208, v96, v92, s[98:99]
	v_cndmask_b32_e64 v209, v97, v93, s[98:99]
	v_cndmask_b32_e64 v92, v92, v96, s[98:99]
	v_cndmask_b32_e64 v93, v93, v97, s[98:99]
	v_mov_b32_dpp v96, v208 quad_perm:[1,0,3,2] row_mask:0xf bank_mask:0xf
	v_mov_b32_dpp v97, v209 quad_perm:[1,0,3,2] row_mask:0xf bank_mask:0xf
	v_pk_add_f32 v[92:93], v[92:93], v[96:97]
	v_cndmask_b32_e64 v208, v178, v204, s[98:99]
	v_cndmask_b32_e64 v209, v179, v205, s[98:99]
	v_cndmask_b32_e64 v204, v204, v178, s[98:99]
	v_cndmask_b32_e64 v205, v205, v179, s[98:99]
	v_mov_b32_dpp v178, v208 quad_perm:[1,0,3,2] row_mask:0xf bank_mask:0xf
	v_mov_b32_dpp v179, v209 quad_perm:[1,0,3,2] row_mask:0xf bank_mask:0xf
	v_pk_add_f32 v[204:205], v[204:205], v[178:179]
	v_cndmask_b32_e64 v208, v76, v60, s[100:101]
	v_cndmask_b32_e64 v209, v77, v61, s[100:101]
	v_cndmask_b32_e64 v60, v60, v76, s[100:101]
	v_cndmask_b32_e64 v61, v61, v77, s[100:101]
	v_mov_b32_dpp v76, v208 quad_perm:[2,3,0,1] row_mask:0xf bank_mask:0xf
	v_mov_b32_dpp v77, v209 quad_perm:[2,3,0,1] row_mask:0xf bank_mask:0xf
	v_pk_add_f32 v[60:61], v[60:61], v[76:77]
	v_cndmask_b32_e64 v208, v204, v92, s[100:101]
	v_cndmask_b32_e64 v209, v205, v93, s[100:101]
	v_cndmask_b32_e64 v92, v92, v204, s[100:101]
	v_cndmask_b32_e64 v93, v93, v205, s[100:101]
	v_mov_b32_dpp v204, v208 quad_perm:[2,3,0,1] row_mask:0xf bank_mask:0xf
	v_mov_b32_dpp v205, v209 quad_perm:[2,3,0,1] row_mask:0xf bank_mask:0xf
	v_pk_add_f32 v[92:93], v[92:93], v[204:205]
	s_nop 1
	v_mov_b32_dpp v208, v60 row_shl:4 row_mask:0xf bank_mask:0x5
	v_mov_b32_dpp v209, v61 row_shl:4 row_mask:0xf bank_mask:0x5
	v_mov_b32_dpp v208, v92 row_shr:4 row_mask:0xf bank_mask:0xa
	v_mov_b32_dpp v209, v93 row_shr:4 row_mask:0xf bank_mask:0xa
	v_mov_b32_dpp v60, v92 quad_perm:[0,1,2,3] row_mask:0xf bank_mask:0xa
	v_mov_b32_dpp v61, v93 quad_perm:[0,1,2,3] row_mask:0xf bank_mask:0xa
	v_pk_add_f32 v[60:61], v[60:61], v[208:209]
	s_nop 0
	v_pk_mul_f32 v[182:183], v[60:61], s[74:75] op_sel_hi:[1,0]
	s_nop 0
	v_fma_f32 v184, -v182, v182, v183
	v_max_f32_e32 v184, 0, v184
	v_add_f32_e32 v184, 0x3727c5ac, v184
	v_cmp_gt_f32_e32 vcc, s75, v184
	v_mul_f32_e32 v185, 0x4b800000, v184
	s_nop 1
	v_cndmask_b32_e32 v184, v184, v185, vcc
	v_rsq_f32_e32 v184, v184
	s_nop 0
	v_mul_f32_e32 v185, 0x45800000, v184
	v_cndmask_b32_e32 v163, v184, v185, vcc
	v_mov_b32_e32 v162, v182
	v_add_co_u32_e32 v196, vcc, 0x4000, v196
	s_nop 1
	v_addc_co_u32_e32 v197, vcc, 0, v197, vcc
	v_add_co_u32_e32 v212, vcc, 0x1000, v196
	s_nop 1
	v_addc_co_u32_e32 v213, vcc, 0, v197, vcc
	global_load_dwordx4 v[60:63], v[196:197], off
	global_load_dwordx4 v[72:75], v[196:197], off offset:1024
	global_load_dwordx4 v[76:79], v[196:197], off offset:2048
	global_load_dwordx4 v[80:83], v[196:197], off offset:3072
	global_load_dwordx4 v[92:95], v[212:213], off
	global_load_dwordx4 v[96:99], v[212:213], off offset:1024
	global_load_dwordx4 v[204:207], v[212:213], off offset:2048
	global_load_dwordx4 v[178:181], v[212:213], off offset:3072
	s_waitcnt vmcnt(0)
	v_pk_add_f32 v[60:61], v[60:61], v[62:63]
	v_pk_add_f32 v[72:73], v[72:73], v[74:75]
	v_pk_add_f32 v[76:77], v[76:77], v[78:79]
	v_pk_add_f32 v[80:81], v[80:81], v[82:83]
	v_pk_add_f32 v[92:93], v[92:93], v[94:95]
	v_pk_add_f32 v[96:97], v[96:97], v[98:99]
	v_pk_add_f32 v[204:205], v[204:205], v[206:207]
	v_pk_add_f32 v[178:179], v[178:179], v[180:181]
	v_cndmask_b32_e64 v208, v72, v60, s[98:99]
	v_cndmask_b32_e64 v209, v73, v61, s[98:99]
	v_cndmask_b32_e64 v60, v60, v72, s[98:99]
	v_cndmask_b32_e64 v61, v61, v73, s[98:99]
	v_mov_b32_dpp v72, v208 quad_perm:[1,0,3,2] row_mask:0xf bank_mask:0xf
	v_mov_b32_dpp v73, v209 quad_perm:[1,0,3,2] row_mask:0xf bank_mask:0xf
	v_pk_add_f32 v[60:61], v[60:61], v[72:73]
	v_cndmask_b32_e64 v208, v80, v76, s[98:99]
	v_cndmask_b32_e64 v209, v81, v77, s[98:99]
	v_cndmask_b32_e64 v76, v76, v80, s[98:99]
	v_cndmask_b32_e64 v77, v77, v81, s[98:99]
	v_mov_b32_dpp v80, v208 quad_perm:[1,0,3,2] row_mask:0xf bank_mask:0xf
	v_mov_b32_dpp v81, v209 quad_perm:[1,0,3,2] row_mask:0xf bank_mask:0xf
	v_pk_add_f32 v[76:77], v[76:77], v[80:81]
	v_cndmask_b32_e64 v208, v96, v92, s[98:99]
	v_cndmask_b32_e64 v209, v97, v93, s[98:99]
	v_cndmask_b32_e64 v92, v92, v96, s[98:99]
	v_cndmask_b32_e64 v93, v93, v97, s[98:99]
	v_mov_b32_dpp v96, v208 quad_perm:[1,0,3,2] row_mask:0xf bank_mask:0xf
	v_mov_b32_dpp v97, v209 quad_perm:[1,0,3,2] row_mask:0xf bank_mask:0xf
	v_pk_add_f32 v[92:93], v[92:93], v[96:97]
	v_cndmask_b32_e64 v208, v178, v204, s[98:99]
	v_cndmask_b32_e64 v209, v179, v205, s[98:99]
; __device__ __forceinline__ void row_stats(const float* st, int row, int fq, float& mu, float& rs) {
;     const f32x4 a = *(const f32x4*)(st + (size_t)row * 32 + fq * 8), b = *(const f32x4*)(st + (size_t)row * 32 + fq * 8 + 4);
;     float s = (a[0] + a[2]) + (b[0] + b[2]), q = (a[1] + a[3]) + (b[1] + b[3]);
;     s += __shfl_xor(s, 16); s += __shfl_xor(s, 32); q += __shfl_xor(q, 16); q += __shfl_xor(q, 32);
;     mu = s * (1.0f / 1024.0f); const float var = fmaxf(q * (1.0f / 1024.0f) - mu * mu, 0.f); rs = rsqrtf(var + LN_EPS);
;     __device__ __forceinline__ void operator()(const f32x4 (&acc)[2][2][4][2], const Unit& u, int wr, int wc, int fr_, int fq_) const {
;     ...
;             for (int n = 0; n < 2; ++n) { c1v[bj][n] = *(const f32x4*)(c1 + u.pn * 256 + bj * 128 + lc + 4 * n); c2v[bj][n] = *(const f32x4*)(c2 + u.pn * 256 + bj * 128 + lc + 4 * n); }
;         float mus[8], rss[8];
; #pragma unroll
;         for (int q = 0; q < 8; ++q) row_stats(st1, u.pm * 256 + (q >> 2) * 128 + (q & 3) * 16 + wr * 64 + fr, fq, mus[q], rss[q]);
;         asm volatile("" ::: "memory");
; #pragma unroll
;         for (int ai = 0; ai < 2; ++ai)
; #pragma unroll
;             for (int m = 0; m < 4; ++m) {
;                 const int grow = u.pm * 256 + ai * 128 + m * 16 + wr * 64 + fr;
;                 const float mu = mus[ai * 4 + m], rs = rss[ai * 4 + m];
;                 f32x4 h[2];
; #pragma unroll
;                 for (int n = 0; n < 2; ++n) {
;                     const f32x4 g = (acc[ai][0][m][n] - mu * c1v[0][n]) * rs + c2v[0][n];
;                     const f32x4 up = (acc[ai][1][m][n] - mu * c1v[1][n]) * rs + c2v[1][n];
	v_cndmask_b32_e64 v204, v204, v178, s[98:99]
	v_cndmask_b32_e64 v205, v205, v179, s[98:99]
	v_mov_b32_dpp v178, v208 quad_perm:[1,0,3,2] row_mask:0xf bank_mask:0xf
	v_mov_b32_dpp v179, v209 quad_perm:[1,0,3,2] row_mask:0xf bank_mask:0xf
	v_pk_add_f32 v[204:205], v[204:205], v[178:179]
	v_cndmask_b32_e64 v208, v76, v60, s[100:101]
	v_cndmask_b32_e64 v209, v77, v61, s[100:101]
	v_cndmask_b32_e64 v60, v60, v76, s[100:101]
	v_cndmask_b32_e64 v61, v61, v77, s[100:101]
	v_mov_b32_dpp v76, v208 quad_perm:[2,3,0,1] row_mask:0xf bank_mask:0xf
	v_mov_b32_dpp v77, v209 quad_perm:[2,3,0,1] row_mask:0xf bank_mask:0xf
	v_pk_add_f32 v[60:61], v[60:61], v[76:77]
	v_cndmask_b32_e64 v208, v204, v92, s[100:101]
	v_cndmask_b32_e64 v209, v205, v93, s[100:101]
	v_cndmask_b32_e64 v92, v92, v204, s[100:101]
	v_cndmask_b32_e64 v93, v93, v205, s[100:101]
	v_mov_b32_dpp v204, v208 quad_perm:[2,3,0,1] row_mask:0xf bank_mask:0xf
	v_mov_b32_dpp v205, v209 quad_perm:[2,3,0,1] row_mask:0xf bank_mask:0xf
	v_pk_add_f32 v[92:93], v[92:93], v[204:205]
	s_nop 1
	v_mov_b32_dpp v208, v60 row_shl:4 row_mask:0xf bank_mask:0x5
	v_mov_b32_dpp v209, v61 row_shl:4 row_mask:0xf bank_mask:0x5
	v_mov_b32_dpp v208, v92 row_shr:4 row_mask:0xf bank_mask:0xa
	v_mov_b32_dpp v209, v93 row_shr:4 row_mask:0xf bank_mask:0xa
	v_mov_b32_dpp v60, v92 quad_perm:[0,1,2,3] row_mask:0xf bank_mask:0xa
	v_mov_b32_dpp v61, v93 quad_perm:[0,1,2,3] row_mask:0xf bank_mask:0xa
	v_pk_add_f32 v[60:61], v[60:61], v[208:209]
	s_nop 0
	v_pk_mul_f32 v[182:183], v[60:61], s[74:75] op_sel_hi:[1,0]
	s_nop 0
	v_fma_f32 v184, -v182, v182, v183
	v_max_f32_e32 v184, 0, v184
	v_add_f32_e32 v184, 0x3727c5ac, v184
	v_cmp_gt_f32_e32 vcc, s75, v184
	v_mul_f32_e32 v185, 0x4b800000, v184
	s_nop 1
	v_cndmask_b32_e32 v184, v184, v185, vcc
	v_rsq_f32_e32 v184, v184
	s_nop 0
	v_mul_f32_e32 v185, 0x45800000, v184
	v_cndmask_b32_e32 v165, v184, v185, vcc
	v_mov_b32_e32 v164, v182
	global_load_dwordx4 v[72:75], v[64:65], off offset:16
	global_load_dwordx4 v[92:95], v[64:65], off
	global_load_dwordx4 v[76:79], v[84:85], off offset:16
	global_load_dwordx4 v[96:99], v[84:85], off
	global_load_dwordx4 v[60:63], v[64:65], off offset:528
	global_load_dwordx4 v[80:83], v[64:65], off offset:512
	s_nop 0
	global_load_dwordx4 v[64:67], v[84:85], off offset:528
	s_nop 0
	global_load_dwordx4 v[84:87], v[84:85], off offset:512
	v_and_b32_e32 v194, 15, v231
	v_and_b32_e32 v195, 7, v194
	v_lshrrev_b32_e32 v194, 3, v194
	v_lshlrev_b32_e32 v194, 2, v194
	v_lshl_add_u32 v194, v195, 5, v194
	v_add_u32_e32 v195, 8, v194
	v_add_u32_e32 v196, 16, v194
	v_add_u32_e32 v197, 24, v194
	ds_bpermute_b32 v227, v194, v162
	ds_bpermute_b32 v228, v194, v163
	ds_bpermute_b32 v215, v195, v162
	ds_bpermute_b32 v216, v195, v163
	ds_bpermute_b32 v201, v196, v162
	ds_bpermute_b32 v202, v196, v163
	ds_bpermute_b32 v199, v197, v162
	ds_bpermute_b32 v192, v197, v163
	ds_bpermute_b32 v181, v194, v164
	ds_bpermute_b32 v186, v194, v165
	ds_bpermute_b32 v219, v195, v164
	ds_bpermute_b32 v222, v195, v165
	ds_bpermute_b32 v221, v196, v164
	ds_bpermute_b32 v224, v196, v165
	ds_bpermute_b32 v208, v197, v164
	ds_bpermute_b32 v209, v197, v165
	s_waitcnt lgkmcnt(0)
	v_mov_b32_e32 v161, v208
	v_mov_b32_e32 v162, v209
	s_waitcnt vmcnt(0)
	v_add_u32_e32 v204, 16, v210
	v_ashrrev_i32_e32 v205, 31, v204
	v_add_u32_e32 v208, 0x90, v210
	v_ashrrev_i32_e32 v209, 31, v208
	v_add_u32_e32 v212, 0xa0, v210
	v_ashrrev_i32_e32 v213, 31, v212
	s_lshl_b32 s10, s54, 7
	s_ashr_i32 s11, s10, 31
	s_movk_i32 s1, 0x1600
	s_lshl_b64 s[10:11], s[10:11], 1
	s_mov_b32 s54, s0
	s_mov_b32 s5, s38
	v_pk_fma_f32 v[156:157], v[92:93], v[226:227], v[156:157] op_sel:[0,1,0] neg_lo:[1,0,0] neg_hi:[1,0,0]
	v_pk_fma_f32 v[152:153], v[80:81], v[226:227], v[152:153] op_sel:[0,1,0] neg_lo:[1,0,0] neg_hi:[1,0,0]
	v_pk_fma_f32 v[154:155], v[82:83], v[226:227], v[154:155] op_sel:[0,1,0] neg_lo:[1,0,0] neg_hi:[1,0,0]
	v_pk_fma_f32 v[148:149], v[72:73], v[226:227], v[148:149] op_sel:[0,1,0] neg_lo:[1,0,0] neg_hi:[1,0,0]
	v_pk_fma_f32 v[156:157], v[156:157], v[228:229], v[96:97] op_sel_hi:[1,0,1]
	v_pk_fma_f32 v[152:153], v[152:153], v[228:229], v[84:85] op_sel_hi:[1,0,1]
	v_pk_fma_f32 v[154:155], v[154:155], v[228:229], v[86:87] op_sel_hi:[1,0,1]
	v_pk_fma_f32 v[148:149], v[148:149], v[228:229], v[76:77] op_sel_hi:[1,0,1]
	v_pk_fma_f32 v[144:145], v[60:61], v[226:227], v[144:145] op_sel:[0,1,0] neg_lo:[1,0,0] neg_hi:[1,0,0]
	v_pk_fma_f32 v[146:147], v[62:63], v[226:227], v[146:147] op_sel:[0,1,0] neg_lo:[1,0,0] neg_hi:[1,0,0]
	v_pk_fma_f32 v[144:145], v[144:145], v[228:229], v[64:65] op_sel_hi:[1,0,1]
	v_pk_fma_f32 v[146:147], v[146:147], v[228:229], v[66:67] op_sel_hi:[1,0,1]
	v_add_u32_e32 v182, 32, v210
	v_ashrrev_i32_e32 v183, 31, v182
	v_pk_fma_f32 v[140:141], v[92:93], v[214:215], v[140:141] op_sel:[0,1,0] neg_lo:[1,0,0] neg_hi:[1,0,0]
	v_pk_fma_f32 v[136:137], v[80:81], v[214:215], v[136:137] op_sel:[0,1,0] neg_lo:[1,0,0] neg_hi:[1,0,0]
	v_pk_fma_f32 v[138:139], v[82:83], v[214:215], v[138:139] op_sel:[0,1,0] neg_lo:[1,0,0] neg_hi:[1,0,0]
	v_pk_fma_f32 v[132:133], v[72:73], v[214:215], v[132:133] op_sel:[0,1,0] neg_lo:[1,0,0] neg_hi:[1,0,0]
	v_pk_fma_f32 v[140:141], v[140:141], v[216:217], v[96:97] op_sel_hi:[1,0,1]
	v_pk_fma_f32 v[136:137], v[136:137], v[216:217], v[84:85] op_sel_hi:[1,0,1]
	v_pk_fma_f32 v[138:139], v[138:139], v[216:217], v[86:87] op_sel_hi:[1,0,1]
	v_pk_fma_f32 v[132:133], v[132:133], v[216:217], v[76:77] op_sel_hi:[1,0,1]
	v_pk_fma_f32 v[128:129], v[60:61], v[214:215], v[128:129] op_sel:[0,1,0] neg_lo:[1,0,0] neg_hi:[1,0,0]
	v_pk_fma_f32 v[130:131], v[62:63], v[214:215], v[130:131] op_sel:[0,1,0] neg_lo:[1,0,0] neg_hi:[1,0,0]
;     __device__ __forceinline__ void operator()(const f32x4 (&acc)[2][2][4][2], const Unit& u, int wr, int wc, int fr_, int fq_) const {
;     ...
;             for (int m = 0; m < 4; ++m) {
;                 const int grow = u.pm * 256 + ai * 128 + m * 16 + wr * 64 + fr;
;                 const float mu = mus[ai * 4 + m], rs = rss[ai * 4 + m];
;                 f32x4 h[2];
; #pragma unroll
;                 for (int n = 0; n < 2; ++n) {
;                     const f32x4 g = (acc[ai][0][m][n] - mu * c1v[0][n]) * rs + c2v[0][n];
;                     const f32x4 up = (acc[ai][1][m][n] - mu * c1v[1][n]) * rs + c2v[1][n];
	v_pk_fma_f32 v[128:129], v[128:129], v[216:217], v[64:65] op_sel_hi:[1,0,1]
	v_pk_fma_f32 v[130:131], v[130:131], v[216:217], v[66:67] op_sel_hi:[1,0,1]
	v_add_u32_e32 v184, 48, v210
	v_ashrrev_i32_e32 v185, 31, v184
	v_pk_fma_f32 v[124:125], v[92:93], v[200:201], v[124:125] op_sel:[0,1,0] neg_lo:[1,0,0] neg_hi:[1,0,0]
	v_pk_fma_f32 v[120:121], v[80:81], v[200:201], v[120:121] op_sel:[0,1,0] neg_lo:[1,0,0] neg_hi:[1,0,0]
	v_pk_fma_f32 v[122:123], v[82:83], v[200:201], v[122:123] op_sel:[0,1,0] neg_lo:[1,0,0] neg_hi:[1,0,0]
	v_pk_fma_f32 v[116:117], v[72:73], v[200:201], v[116:117] op_sel:[0,1,0] neg_lo:[1,0,0] neg_hi:[1,0,0]
	v_pk_fma_f32 v[124:125], v[124:125], v[202:203], v[96:97] op_sel_hi:[1,0,1]
	v_pk_fma_f32 v[120:121], v[120:121], v[202:203], v[84:85] op_sel_hi:[1,0,1]
	v_pk_fma_f32 v[122:123], v[122:123], v[202:203], v[86:87] op_sel_hi:[1,0,1]
	v_pk_fma_f32 v[116:117], v[116:117], v[202:203], v[76:77] op_sel_hi:[1,0,1]
	v_pk_fma_f32 v[112:113], v[60:61], v[200:201], v[112:113] op_sel:[0,1,0] neg_lo:[1,0,0] neg_hi:[1,0,0]
	v_pk_fma_f32 v[114:115], v[62:63], v[200:201], v[114:115] op_sel:[0,1,0] neg_lo:[1,0,0] neg_hi:[1,0,0]
	v_pk_fma_f32 v[112:113], v[112:113], v[202:203], v[64:65] op_sel_hi:[1,0,1]
	v_pk_fma_f32 v[114:115], v[114:115], v[202:203], v[66:67] op_sel_hi:[1,0,1]
	v_add_u32_e32 v178, 0x80, v210
	v_ashrrev_i32_e32 v179, 31, v178
	v_pk_fma_f32 v[108:109], v[92:93], v[198:199], v[108:109] op_sel:[0,1,0] neg_lo:[1,0,0] neg_hi:[1,0,0]
	v_pk_fma_f32 v[104:105], v[80:81], v[198:199], v[104:105] op_sel:[0,1,0] neg_lo:[1,0,0] neg_hi:[1,0,0]
	v_pk_fma_f32 v[106:107], v[82:83], v[198:199], v[106:107] op_sel:[0,1,0] neg_lo:[1,0,0] neg_hi:[1,0,0]
	v_pk_fma_f32 v[100:101], v[72:73], v[198:199], v[100:101] op_sel:[0,1,0] neg_lo:[1,0,0] neg_hi:[1,0,0]
	v_pk_fma_f32 v[108:109], v[108:109], v[192:193], v[96:97] op_sel_hi:[1,0,1]
	v_pk_fma_f32 v[104:105], v[104:105], v[192:193], v[84:85] op_sel_hi:[1,0,1]
	v_pk_fma_f32 v[106:107], v[106:107], v[192:193], v[86:87] op_sel_hi:[1,0,1]
	v_pk_fma_f32 v[100:101], v[100:101], v[192:193], v[76:77] op_sel_hi:[1,0,1]
	v_pk_fma_f32 v[88:89], v[60:61], v[198:199], v[88:89] op_sel:[0,1,0] neg_lo:[1,0,0] neg_hi:[1,0,0]
	v_pk_fma_f32 v[90:91], v[62:63], v[198:199], v[90:91] op_sel:[0,1,0] neg_lo:[1,0,0] neg_hi:[1,0,0]
	v_pk_fma_f32 v[88:89], v[88:89], v[192:193], v[64:65] op_sel_hi:[1,0,1]
	v_pk_fma_f32 v[90:91], v[90:91], v[192:193], v[66:67] op_sel_hi:[1,0,1]
	v_pk_fma_f32 v[68:69], v[92:93], v[180:181], v[68:69] op_sel:[0,1,0] neg_lo:[1,0,0] neg_hi:[1,0,0]
	v_pk_fma_f32 v[56:57], v[80:81], v[180:181], v[56:57] op_sel:[0,1,0] neg_lo:[1,0,0] neg_hi:[1,0,0]
	v_pk_fma_f32 v[58:59], v[82:83], v[180:181], v[58:59] op_sel:[0,1,0] neg_lo:[1,0,0] neg_hi:[1,0,0]
	v_pk_fma_f32 v[52:53], v[72:73], v[180:181], v[52:53] op_sel:[0,1,0] neg_lo:[1,0,0] neg_hi:[1,0,0]
	v_pk_fma_f32 v[68:69], v[68:69], v[186:187], v[96:97] op_sel_hi:[1,0,1]
	v_pk_fma_f32 v[56:57], v[56:57], v[186:187], v[84:85] op_sel_hi:[1,0,1]
	v_pk_fma_f32 v[58:59], v[58:59], v[186:187], v[86:87] op_sel_hi:[1,0,1]
	v_pk_fma_f32 v[52:53], v[52:53], v[186:187], v[76:77] op_sel_hi:[1,0,1]
	v_pk_fma_f32 v[48:49], v[60:61], v[180:181], v[48:49] op_sel:[0,1,0] neg_lo:[1,0,0] neg_hi:[1,0,0]
	v_pk_fma_f32 v[50:51], v[62:63], v[180:181], v[50:51] op_sel:[0,1,0] neg_lo:[1,0,0] neg_hi:[1,0,0]
	v_pk_fma_f32 v[48:49], v[48:49], v[186:187], v[64:65] op_sel_hi:[1,0,1]
	v_pk_fma_f32 v[50:51], v[50:51], v[186:187], v[66:67] op_sel_hi:[1,0,1]
	v_pk_fma_f32 v[44:45], v[92:93], v[218:219], v[44:45] op_sel:[0,1,0] neg_lo:[1,0,0] neg_hi:[1,0,0]
	v_pk_fma_f32 v[40:41], v[80:81], v[218:219], v[40:41] op_sel:[0,1,0] neg_lo:[1,0,0] neg_hi:[1,0,0]
	v_pk_fma_f32 v[42:43], v[82:83], v[218:219], v[42:43] op_sel:[0,1,0] neg_lo:[1,0,0] neg_hi:[1,0,0]
	v_pk_fma_f32 v[36:37], v[72:73], v[218:219], v[36:37] op_sel:[0,1,0] neg_lo:[1,0,0] neg_hi:[1,0,0]
	v_pk_fma_f32 v[44:45], v[44:45], v[222:223], v[96:97] op_sel_hi:[1,0,1]
	v_pk_fma_f32 v[40:41], v[40:41], v[222:223], v[84:85] op_sel_hi:[1,0,1]
	v_pk_fma_f32 v[42:43], v[42:43], v[222:223], v[86:87] op_sel_hi:[1,0,1]
	v_pk_fma_f32 v[36:37], v[36:37], v[222:223], v[76:77] op_sel_hi:[1,0,1]
	v_pk_fma_f32 v[32:33], v[60:61], v[218:219], v[32:33] op_sel:[0,1,0] neg_lo:[1,0,0] neg_hi:[1,0,0]
	v_pk_fma_f32 v[34:35], v[62:63], v[218:219], v[34:35] op_sel:[0,1,0] neg_lo:[1,0,0] neg_hi:[1,0,0]
	v_pk_fma_f32 v[32:33], v[32:33], v[222:223], v[64:65] op_sel_hi:[1,0,1]
	v_pk_fma_f32 v[34:35], v[34:35], v[222:223], v[66:67] op_sel_hi:[1,0,1]
	v_add_u32_e32 v206, 0xb0, v210
	v_ashrrev_i32_e32 v207, 31, v206
	v_pk_fma_f32 v[28:29], v[92:93], v[220:221], v[28:29] op_sel:[0,1,0] neg_lo:[1,0,0] neg_hi:[1,0,0]
	v_pk_fma_f32 v[24:25], v[80:81], v[220:221], v[24:25] op_sel:[0,1,0] neg_lo:[1,0,0] neg_hi:[1,0,0]
	v_pk_fma_f32 v[26:27], v[82:83], v[220:221], v[26:27] op_sel:[0,1,0] neg_lo:[1,0,0] neg_hi:[1,0,0]
	v_pk_fma_f32 v[20:21], v[72:73], v[220:221], v[20:21] op_sel:[0,1,0] neg_lo:[1,0,0] neg_hi:[1,0,0]
	v_pk_fma_f32 v[28:29], v[28:29], v[224:225], v[96:97] op_sel_hi:[1,0,1]
	v_pk_fma_f32 v[24:25], v[24:25], v[224:225], v[84:85] op_sel_hi:[1,0,1]
	v_pk_fma_f32 v[26:27], v[26:27], v[224:225], v[86:87] op_sel_hi:[1,0,1]
	v_pk_fma_f32 v[20:21], v[20:21], v[224:225], v[76:77] op_sel_hi:[1,0,1]
	v_pk_fma_f32 v[16:17], v[60:61], v[220:221], v[16:17] op_sel:[0,1,0] neg_lo:[1,0,0] neg_hi:[1,0,0]
	v_pk_fma_f32 v[18:19], v[62:63], v[220:221], v[18:19] op_sel:[0,1,0] neg_lo:[1,0,0] neg_hi:[1,0,0]
	v_pk_fma_f32 v[16:17], v[16:17], v[224:225], v[64:65] op_sel_hi:[1,0,1]
	v_pk_fma_f32 v[18:19], v[18:19], v[224:225], v[66:67] op_sel_hi:[1,0,1]
; __device__ __forceinline__ float silu_f(float x) { return x * __builtin_amdgcn_rcpf(1.0f + __expf(-x)); }
; __device__ __forceinline__ u32x4 pack8(const f32x4 a, const f32x4 b) { u32x4 w; w.x = cvt_pk_bf16(a[0], a[1]); w.y = cvt_pk_bf16(a[2], a[3]); w.z = cvt_pk_bf16(b[0], b[1]); w.w = cvt_pk_bf16(b[2], b[3]); return w; }
;     __device__ __forceinline__ void operator()(const f32x4 (&acc)[2][2][4][2], const Unit& u, int wr, int wc, int fr_, int fq_) const {
;     ...
;             for (int m = 0; m < 4; ++m) {
;                 const int grow = u.pm * 256 + ai * 128 + m * 16 + wr * 64 + fr;
;                 const float mu = mus[ai * 4 + m], rs = rss[ai * 4 + m];
;                 f32x4 h[2];
; #pragma unroll
;                 for (int n = 0; n < 2; ++n) {
;                     const f32x4 g = (acc[ai][0][m][n] - mu * c1v[0][n]) * rs + c2v[0][n];
;                     const f32x4 up = (acc[ai][1][m][n] - mu * c1v[1][n]) * rs + c2v[1][n];
; #pragma unroll
;                     for (int j = 0; j < 4; ++j) h[n][j] = silu_f(g[j]) * up[j];
;                 }
;                 *(u32x4*)(H + (size_t)grow * KF2 + u.pn * 128 + lc) = pack8(h[0], h[1]);
	v_pk_fma_f32 v[12:13], v[92:93], v[160:161], v[12:13] op_sel:[0,1,0] neg_lo:[1,0,0] neg_hi:[1,0,0]
	v_pk_fma_f32 v[8:9], v[80:81], v[160:161], v[8:9] op_sel:[0,1,0] neg_lo:[1,0,0] neg_hi:[1,0,0]
	v_pk_fma_f32 v[10:11], v[82:83], v[160:161], v[10:11] op_sel:[0,1,0] neg_lo:[1,0,0] neg_hi:[1,0,0]
	v_pk_fma_f32 v[4:5], v[72:73], v[160:161], v[4:5] op_sel:[0,1,0] neg_lo:[1,0,0] neg_hi:[1,0,0]
	v_mul_f32_e32 v163, 0xbfb8aa3b, v156
	v_exp_f32_e32 v163, v163
	v_pk_fma_f32 v[0:1], v[60:61], v[160:161], v[0:1] op_sel:[0,1,0] neg_lo:[1,0,0] neg_hi:[1,0,0]
	v_pk_fma_f32 v[2:3], v[62:63], v[160:161], v[2:3] op_sel:[0,1,0] neg_lo:[1,0,0] neg_hi:[1,0,0]
	s_and_b64 vcc, exec, s[40:41]
	v_add_f32_e32 v163, 1.0, v163
	v_rcp_f32_e32 v164, v163
	v_mul_f32_e32 v163, 0xbfb8aa3b, v157
	v_exp_f32_e32 v163, v163
	s_nop 0
	v_add_f32_e32 v163, 1.0, v163
	v_rcp_f32_e32 v165, v163
	v_pk_fma_f32 v[12:13], v[12:13], v[162:163], v[96:97] op_sel_hi:[1,0,1]
	v_pk_fma_f32 v[8:9], v[8:9], v[162:163], v[84:85] op_sel_hi:[1,0,1]
	v_pk_fma_f32 v[10:11], v[10:11], v[162:163], v[86:87] op_sel_hi:[1,0,1]
	v_pk_mul_f32 v[156:157], v[156:157], v[164:165]
	v_pk_fma_f32 v[4:5], v[4:5], v[162:163], v[76:77] op_sel_hi:[1,0,1]
	v_pk_mul_f32 v[152:153], v[152:153], v[156:157]
	v_pk_fma_f32 v[156:157], v[94:95], v[226:227], v[158:159] op_sel:[0,1,0] neg_lo:[1,0,0] neg_hi:[1,0,0]
	v_pk_fma_f32 v[0:1], v[0:1], v[162:163], v[64:65] op_sel_hi:[1,0,1]
	v_pk_fma_f32 v[156:157], v[156:157], v[228:229], v[98:99] op_sel_hi:[1,0,1]
	v_pk_fma_f32 v[2:3], v[2:3], v[162:163], v[66:67] op_sel_hi:[1,0,1]
	v_mul_f32_e32 v158, 0xbfb8aa3b, v156
	v_mul_f32_e32 v159, 0xbfb8aa3b, v157
	v_exp_f32_e32 v158, v158
	v_exp_f32_e32 v159, v159
	v_add_f32_e32 v158, 1.0, v158
	v_add_f32_e32 v159, 1.0, v159
	v_rcp_f32_e32 v158, v158
	v_rcp_f32_e32 v159, v159
	s_nop 0
	v_pk_mul_f32 v[156:157], v[156:157], v[158:159]
	s_nop 0
	v_pk_mul_f32 v[154:155], v[154:155], v[156:157]
	v_mul_f32_e32 v156, 0xbfb8aa3b, v148
	v_mul_f32_e32 v157, 0xbfb8aa3b, v149
	v_exp_f32_e32 v156, v156
	v_exp_f32_e32 v157, v157
	v_add_f32_e32 v156, 1.0, v156
	v_add_f32_e32 v157, 1.0, v157
	v_rcp_f32_e32 v156, v156
	v_rcp_f32_e32 v157, v157
	s_nop 0
	v_pk_mul_f32 v[148:149], v[148:149], v[156:157]
	s_nop 0
	v_pk_mul_f32 v[144:145], v[144:145], v[148:149]
	v_pk_fma_f32 v[148:149], v[74:75], v[226:227], v[150:151] op_sel:[0,1,0] neg_lo:[1,0,0] neg_hi:[1,0,0]
	s_nop 0
	v_pk_fma_f32 v[148:149], v[148:149], v[228:229], v[78:79] op_sel_hi:[1,0,1]
	s_nop 0
	v_mul_f32_e32 v150, 0xbfb8aa3b, v148
	v_mul_f32_e32 v151, 0xbfb8aa3b, v149
	v_exp_f32_e32 v150, v150
	v_exp_f32_e32 v151, v151
	v_add_f32_e32 v150, 1.0, v150
	v_add_f32_e32 v151, 1.0, v151
	v_rcp_f32_e32 v150, v150
	v_rcp_f32_e32 v151, v151
	s_nop 0
	v_pk_mul_f32 v[148:149], v[148:149], v[150:151]
	s_nop 0
	v_pk_mul_f32 v[146:147], v[146:147], v[148:149]
	v_cvt_pk_bf16_f32 v150, v144, v145
	v_mov_b64_e32 v[144:145], s[24:25]
	v_cvt_pk_bf16_f32 v151, v146, v147
	v_mad_i64_i32 v[146:147], s[14:15], v210, s1, v[144:145]
	v_cvt_pk_bf16_f32 v148, v152, v153
	v_lshl_add_u64 v[152:153], v[146:147], 0, s[10:11]
	v_lshlrev_b64 v[146:147], 1, v[188:189]
	v_cvt_pk_bf16_f32 v149, v154, v155
	v_lshl_add_u64 v[152:153], v[152:153], 0, v[146:147]
	global_store_dwordx4 v[152:153], v[148:151], off
	s_nop 1
	v_mul_f32_e32 v148, 0xbfb8aa3b, v140
	v_mul_f32_e32 v149, 0xbfb8aa3b, v141
	v_exp_f32_e32 v148, v148
	v_exp_f32_e32 v149, v149
	v_add_f32_e32 v148, 1.0, v148
	v_add_f32_e32 v149, 1.0, v149
	v_rcp_f32_e32 v148, v148
	v_rcp_f32_e32 v149, v149
	s_nop 0
	v_pk_mul_f32 v[140:141], v[140:141], v[148:149]
	s_nop 0
	v_pk_mul_f32 v[136:137], v[136:137], v[140:141]
	v_pk_fma_f32 v[140:141], v[94:95], v[214:215], v[142:143] op_sel:[0,1,0] neg_lo:[1,0,0] neg_hi:[1,0,0]
	s_nop 0
	v_pk_fma_f32 v[140:141], v[140:141], v[216:217], v[98:99] op_sel_hi:[1,0,1]
	s_nop 0
	v_mul_f32_e32 v142, 0xbfb8aa3b, v140
	v_mul_f32_e32 v143, 0xbfb8aa3b, v141
	v_exp_f32_e32 v142, v142
	v_exp_f32_e32 v143, v143
	v_add_f32_e32 v142, 1.0, v142
	v_add_f32_e32 v143, 1.0, v143
	v_rcp_f32_e32 v142, v142
	v_rcp_f32_e32 v143, v143
	s_nop 0
	v_pk_mul_f32 v[140:141], v[140:141], v[142:143]
	s_nop 0
	v_pk_mul_f32 v[138:139], v[138:139], v[140:141]
	v_mul_f32_e32 v140, 0xbfb8aa3b, v132
	v_mul_f32_e32 v141, 0xbfb8aa3b, v133
	v_exp_f32_e32 v140, v140
	v_exp_f32_e32 v141, v141
	v_add_f32_e32 v140, 1.0, v140
	v_add_f32_e32 v141, 1.0, v141
	v_rcp_f32_e32 v140, v140
	v_rcp_f32_e32 v141, v141
	s_nop 0
	v_pk_mul_f32 v[132:133], v[132:133], v[140:141]
	s_nop 0
	v_pk_mul_f32 v[132:133], v[128:129], v[132:133]
	v_pk_fma_f32 v[128:129], v[74:75], v[214:215], v[134:135] op_sel:[0,1,0] neg_lo:[1,0,0] neg_hi:[1,0,0]
	s_nop 0
	v_pk_fma_f32 v[128:129], v[128:129], v[216:217], v[78:79] op_sel_hi:[1,0,1]
	s_nop 0
	v_mul_f32_e32 v134, 0xbfb8aa3b, v128
	v_mul_f32_e32 v135, 0xbfb8aa3b, v129
	v_exp_f32_e32 v134, v134
	v_exp_f32_e32 v135, v135
	v_add_f32_e32 v134, 1.0, v134
	v_add_f32_e32 v135, 1.0, v135
	v_rcp_f32_e32 v134, v134
	v_rcp_f32_e32 v135, v135
	s_nop 0
	v_pk_mul_f32 v[128:129], v[128:129], v[134:135]
	s_nop 0
	v_pk_mul_f32 v[134:135], v[130:131], v[128:129]
	v_cvt_pk_bf16_f32 v130, v132, v133
	v_mad_i64_i32 v[132:133], s[14:15], v204, s1, v[144:145]
	v_lshl_add_u64 v[132:133], v[132:133], 0, s[10:11]
	v_cvt_pk_bf16_f32 v128, v136, v137
	v_cvt_pk_bf16_f32 v129, v138, v139
	v_cvt_pk_bf16_f32 v131, v134, v135
	v_lshl_add_u64 v[132:133], v[132:133], 0, v[146:147]
	global_store_dwordx4 v[132:133], v[128:131], off
	s_nop 1
	v_mul_f32_e32 v128, 0xbfb8aa3b, v124
	v_mul_f32_e32 v129, 0xbfb8aa3b, v125
	v_exp_f32_e32 v128, v128
	v_exp_f32_e32 v129, v129
	v_add_f32_e32 v128, 1.0, v128
; __device__ __forceinline__ float silu_f(float x) { return x * __builtin_amdgcn_rcpf(1.0f + __expf(-x)); }
; __device__ __forceinline__ u32x4 pack8(const f32x4 a, const f32x4 b) { u32x4 w; w.x = cvt_pk_bf16(a[0], a[1]); w.y = cvt_pk_bf16(a[2], a[3]); w.z = cvt_pk_bf16(b[0], b[1]); w.w = cvt_pk_bf16(b[2], b[3]); return w; }
;     __device__ __forceinline__ void operator()(const f32x4 (&acc)[2][2][4][2], const Unit& u, int wr, int wc, int fr_, int fq_) const {
;     ...
;             for (int m = 0; m < 4; ++m) {
;                 const int grow = u.pm * 256 + ai * 128 + m * 16 + wr * 64 + fr;
;                 const float mu = mus[ai * 4 + m], rs = rss[ai * 4 + m];
;                 f32x4 h[2];
; #pragma unroll
;                 for (int n = 0; n < 2; ++n) {
;                     const f32x4 g = (acc[ai][0][m][n] - mu * c1v[0][n]) * rs + c2v[0][n];
;                     const f32x4 up = (acc[ai][1][m][n] - mu * c1v[1][n]) * rs + c2v[1][n];
; #pragma unroll
;                     for (int j = 0; j < 4; ++j) h[n][j] = silu_f(g[j]) * up[j];
;                 }
;                 *(u32x4*)(H + (size_t)grow * KF2 + u.pn * 128 + lc) = pack8(h[0], h[1]);
	v_add_f32_e32 v129, 1.0, v129
	v_rcp_f32_e32 v128, v128
	v_rcp_f32_e32 v129, v129
	s_nop 0
	v_pk_mul_f32 v[124:125], v[124:125], v[128:129]
	s_nop 0
	v_pk_mul_f32 v[120:121], v[120:121], v[124:125]
	v_pk_fma_f32 v[124:125], v[94:95], v[200:201], v[126:127] op_sel:[0,1,0] neg_lo:[1,0,0] neg_hi:[1,0,0]
	s_nop 0
	v_pk_fma_f32 v[124:125], v[124:125], v[202:203], v[98:99] op_sel_hi:[1,0,1]
	s_nop 0
	v_mul_f32_e32 v126, 0xbfb8aa3b, v124
	v_mul_f32_e32 v127, 0xbfb8aa3b, v125
	v_exp_f32_e32 v126, v126
	v_exp_f32_e32 v127, v127
	v_add_f32_e32 v126, 1.0, v126
	v_add_f32_e32 v127, 1.0, v127
	v_rcp_f32_e32 v126, v126
	v_rcp_f32_e32 v127, v127
	s_nop 0
	v_pk_mul_f32 v[124:125], v[124:125], v[126:127]
	s_nop 0
	v_pk_mul_f32 v[122:123], v[122:123], v[124:125]
	v_mul_f32_e32 v124, 0xbfb8aa3b, v116
	v_mul_f32_e32 v125, 0xbfb8aa3b, v117
	v_exp_f32_e32 v124, v124
	v_exp_f32_e32 v125, v125
	v_add_f32_e32 v124, 1.0, v124
	v_add_f32_e32 v125, 1.0, v125
	v_rcp_f32_e32 v124, v124
	v_rcp_f32_e32 v125, v125
	s_nop 0
	v_pk_mul_f32 v[116:117], v[116:117], v[124:125]
	s_nop 0
	v_pk_mul_f32 v[116:117], v[112:113], v[116:117]
	v_pk_fma_f32 v[112:113], v[74:75], v[200:201], v[118:119] op_sel:[0,1,0] neg_lo:[1,0,0] neg_hi:[1,0,0]
	s_nop 0
	v_pk_fma_f32 v[112:113], v[112:113], v[202:203], v[78:79] op_sel_hi:[1,0,1]
	s_nop 0
	v_mul_f32_e32 v118, 0xbfb8aa3b, v112
	v_mul_f32_e32 v119, 0xbfb8aa3b, v113
	v_exp_f32_e32 v118, v118
	v_exp_f32_e32 v119, v119
	v_add_f32_e32 v118, 1.0, v118
	v_add_f32_e32 v119, 1.0, v119
	v_rcp_f32_e32 v118, v118
	v_rcp_f32_e32 v119, v119
	s_nop 0
	v_pk_mul_f32 v[112:113], v[112:113], v[118:119]
	s_nop 0
	v_pk_mul_f32 v[118:119], v[114:115], v[112:113]
	v_cvt_pk_bf16_f32 v114, v116, v117
	v_mad_i64_i32 v[116:117], s[14:15], v182, s1, v[144:145]
	v_lshl_add_u64 v[116:117], v[116:117], 0, s[10:11]
	v_cvt_pk_bf16_f32 v112, v120, v121
	v_cvt_pk_bf16_f32 v113, v122, v123
	v_cvt_pk_bf16_f32 v115, v118, v119
	v_lshl_add_u64 v[116:117], v[116:117], 0, v[146:147]
	global_store_dwordx4 v[116:117], v[112:115], off
	s_nop 1
	v_mul_f32_e32 v112, 0xbfb8aa3b, v108
	v_mul_f32_e32 v113, 0xbfb8aa3b, v109
	v_exp_f32_e32 v112, v112
	v_exp_f32_e32 v113, v113
	v_add_f32_e32 v112, 1.0, v112
	v_add_f32_e32 v113, 1.0, v113
	v_rcp_f32_e32 v112, v112
	v_rcp_f32_e32 v113, v113
	s_nop 0
	v_pk_mul_f32 v[108:109], v[108:109], v[112:113]
	s_nop 0
	v_pk_mul_f32 v[104:105], v[104:105], v[108:109]
	v_pk_fma_f32 v[108:109], v[94:95], v[198:199], v[110:111] op_sel:[0,1,0] neg_lo:[1,0,0] neg_hi:[1,0,0]
	s_nop 0
	v_pk_fma_f32 v[108:109], v[108:109], v[192:193], v[98:99] op_sel_hi:[1,0,1]
	s_nop 0
	v_mul_f32_e32 v110, 0xbfb8aa3b, v108
	v_mul_f32_e32 v111, 0xbfb8aa3b, v109
	v_exp_f32_e32 v110, v110
	v_exp_f32_e32 v111, v111
	v_add_f32_e32 v110, 1.0, v110
	v_add_f32_e32 v111, 1.0, v111
	v_rcp_f32_e32 v110, v110
	v_rcp_f32_e32 v111, v111
	s_nop 0
	v_pk_mul_f32 v[108:109], v[108:109], v[110:111]
	s_nop 0
	v_pk_mul_f32 v[106:107], v[106:107], v[108:109]
	v_mul_f32_e32 v108, 0xbfb8aa3b, v100
	v_mul_f32_e32 v109, 0xbfb8aa3b, v101
	v_exp_f32_e32 v108, v108
	v_exp_f32_e32 v109, v109
	v_add_f32_e32 v108, 1.0, v108
	v_add_f32_e32 v109, 1.0, v109
	v_rcp_f32_e32 v108, v108
	v_rcp_f32_e32 v109, v109
	s_nop 0
	v_pk_mul_f32 v[100:101], v[100:101], v[108:109]
	s_nop 0
	v_pk_mul_f32 v[100:101], v[88:89], v[100:101]
	v_pk_fma_f32 v[88:89], v[74:75], v[198:199], v[102:103] op_sel:[0,1,0] neg_lo:[1,0,0] neg_hi:[1,0,0]
	s_nop 0
	v_pk_fma_f32 v[88:89], v[88:89], v[192:193], v[78:79] op_sel_hi:[1,0,1]
	s_nop 0
	v_mul_f32_e32 v102, 0xbfb8aa3b, v88
	v_mul_f32_e32 v103, 0xbfb8aa3b, v89
	v_exp_f32_e32 v102, v102
	v_exp_f32_e32 v103, v103
	v_add_f32_e32 v102, 1.0, v102
	v_add_f32_e32 v103, 1.0, v103
	v_rcp_f32_e32 v102, v102
	v_rcp_f32_e32 v103, v103
	s_nop 0
	v_pk_mul_f32 v[88:89], v[88:89], v[102:103]
	s_nop 0
	v_pk_mul_f32 v[102:103], v[90:91], v[88:89]
	v_cvt_pk_bf16_f32 v90, v100, v101
	v_mad_i64_i32 v[100:101], s[14:15], v184, s1, v[144:145]
	v_lshl_add_u64 v[100:101], v[100:101], 0, s[10:11]
	v_cvt_pk_bf16_f32 v88, v104, v105
	v_cvt_pk_bf16_f32 v89, v106, v107
	v_cvt_pk_bf16_f32 v91, v102, v103
	v_lshl_add_u64 v[100:101], v[100:101], 0, v[146:147]
	global_store_dwordx4 v[100:101], v[88:91], off
	s_nop 1
	v_mul_f32_e32 v88, 0xbfb8aa3b, v68
	v_mul_f32_e32 v89, 0xbfb8aa3b, v69
	v_exp_f32_e32 v88, v88
	v_exp_f32_e32 v89, v89
	v_add_f32_e32 v88, 1.0, v88
	v_add_f32_e32 v89, 1.0, v89
	v_rcp_f32_e32 v88, v88
	v_rcp_f32_e32 v89, v89
	s_nop 0
	v_pk_mul_f32 v[68:69], v[68:69], v[88:89]
	s_nop 0
	v_pk_mul_f32 v[56:57], v[56:57], v[68:69]
	v_pk_fma_f32 v[68:69], v[94:95], v[180:181], v[70:71] op_sel:[0,1,0] neg_lo:[1,0,0] neg_hi:[1,0,0]
	s_nop 0
	v_pk_fma_f32 v[68:69], v[68:69], v[186:187], v[98:99] op_sel_hi:[1,0,1]
	s_nop 0
	v_mul_f32_e32 v70, 0xbfb8aa3b, v68
	v_mul_f32_e32 v71, 0xbfb8aa3b, v69
	v_exp_f32_e32 v70, v70
	v_exp_f32_e32 v71, v71
	v_add_f32_e32 v70, 1.0, v70
	v_add_f32_e32 v71, 1.0, v71
	v_rcp_f32_e32 v70, v70
	v_rcp_f32_e32 v71, v71
	s_nop 0
	v_pk_mul_f32 v[68:69], v[68:69], v[70:71]
	s_nop 0
	v_pk_mul_f32 v[58:59], v[58:59], v[68:69]
	v_mul_f32_e32 v68, 0xbfb8aa3b, v52
	v_mul_f32_e32 v69, 0xbfb8aa3b, v53
	v_exp_f32_e32 v68, v68
	v_exp_f32_e32 v69, v69
	v_add_f32_e32 v68, 1.0, v68
	v_add_f32_e32 v69, 1.0, v69
	v_rcp_f32_e32 v68, v68
	v_rcp_f32_e32 v69, v69
	s_nop 0
	v_pk_mul_f32 v[52:53], v[52:53], v[68:69]
	s_nop 0
	v_pk_mul_f32 v[52:53], v[48:49], v[52:53]
	v_pk_fma_f32 v[48:49], v[74:75], v[180:181], v[54:55] op_sel:[0,1,0] neg_lo:[1,0,0] neg_hi:[1,0,0]
	s_nop 0
	v_pk_fma_f32 v[48:49], v[48:49], v[186:187], v[78:79] op_sel_hi:[1,0,1]
	s_nop 0
	v_mul_f32_e32 v54, 0xbfb8aa3b, v48
	v_mul_f32_e32 v55, 0xbfb8aa3b, v49
; __device__ __forceinline__ float silu_f(float x) { return x * __builtin_amdgcn_rcpf(1.0f + __expf(-x)); }
; #define PG8_WAIT_V(n) asm volatile("s_waitcnt vmcnt(" #n ")" ::: "memory")
; #define PG8_BAR __builtin_amdgcn_s_barrier()
; __device__ __forceinline__ u32x4 pack8(const f32x4 a, const f32x4 b) { u32x4 w; w.x = cvt_pk_bf16(a[0], a[1]); w.y = cvt_pk_bf16(a[2], a[3]); w.z = cvt_pk_bf16(b[0], b[1]); w.w = cvt_pk_bf16(b[2], b[3]); return w; }
; template <class Epi>
; __device__ __forceinline__ void gemm_phase(LAS unsigned char* lds, const Gemm g, const StaticOrder& S, const Epi& E) {
;     ...
;         E(acc, cur, wr, wc, fr, fq);
;         if (!has_next) break;
; #pragma unroll
;         for (int a = 0; a < 2; ++a)
; #pragma unroll
;             for (int b = 0; b < 2; ++b)
; #pragma unroll
;                 for (int m = 0; m < 4; ++m)
; #pragma unroll
;                     for (int n = 0; n < 2; ++n) acc[a][b][m][n] = (f32x4){0.f, 0.f, 0.f, 0.f};
;         cur = nxt; cA = nA; cB = nB; ++ui;
;     }
;     PG8_WAIT_V(0);
;     if (wr == 0) PG8_BAR;
;     PG8_BAR;
;     __device__ __forceinline__ void operator()(const f32x4 (&acc)[2][2][4][2], const Unit& u, int wr, int wc, int fr_, int fq_) const {
;     ...
;             for (int m = 0; m < 4; ++m) {
;                 const int grow = u.pm * 256 + ai * 128 + m * 16 + wr * 64 + fr;
;                 const float mu = mus[ai * 4 + m], rs = rss[ai * 4 + m];
;                 f32x4 h[2];
; #pragma unroll
;                 for (int n = 0; n < 2; ++n) {
;                     const f32x4 g = (acc[ai][0][m][n] - mu * c1v[0][n]) * rs + c2v[0][n];
;                     const f32x4 up = (acc[ai][1][m][n] - mu * c1v[1][n]) * rs + c2v[1][n];
; #pragma unroll
;                     for (int j = 0; j < 4; ++j) h[n][j] = silu_f(g[j]) * up[j];
;                 }
;                 *(u32x4*)(H + (size_t)grow * KF2 + u.pn * 128 + lc) = pack8(h[0], h[1]);
;             }
	v_exp_f32_e32 v54, v54
	v_exp_f32_e32 v55, v55
	v_add_f32_e32 v54, 1.0, v54
	v_add_f32_e32 v55, 1.0, v55
	v_rcp_f32_e32 v54, v54
	v_rcp_f32_e32 v55, v55
	s_nop 0
	v_pk_mul_f32 v[48:49], v[48:49], v[54:55]
	s_nop 0
	v_pk_mul_f32 v[54:55], v[50:51], v[48:49]
	v_cvt_pk_bf16_f32 v50, v52, v53
	v_mad_i64_i32 v[52:53], s[14:15], v178, s1, v[144:145]
	v_lshl_add_u64 v[52:53], v[52:53], 0, s[10:11]
	v_cvt_pk_bf16_f32 v48, v56, v57
	v_cvt_pk_bf16_f32 v49, v58, v59
	v_cvt_pk_bf16_f32 v51, v54, v55
	v_lshl_add_u64 v[52:53], v[52:53], 0, v[146:147]
	global_store_dwordx4 v[52:53], v[48:51], off
	s_nop 1
	v_mul_f32_e32 v48, 0xbfb8aa3b, v44
	v_mul_f32_e32 v49, 0xbfb8aa3b, v45
	v_exp_f32_e32 v48, v48
	v_exp_f32_e32 v49, v49
	v_add_f32_e32 v48, 1.0, v48
	v_add_f32_e32 v49, 1.0, v49
	v_rcp_f32_e32 v48, v48
	v_rcp_f32_e32 v49, v49
	s_nop 0
	v_pk_mul_f32 v[44:45], v[44:45], v[48:49]
	s_nop 0
	v_pk_mul_f32 v[40:41], v[40:41], v[44:45]
	v_pk_fma_f32 v[44:45], v[94:95], v[218:219], v[46:47] op_sel:[0,1,0] neg_lo:[1,0,0] neg_hi:[1,0,0]
	s_nop 0
	v_pk_fma_f32 v[44:45], v[44:45], v[222:223], v[98:99] op_sel_hi:[1,0,1]
	s_nop 0
	v_mul_f32_e32 v46, 0xbfb8aa3b, v44
	v_mul_f32_e32 v47, 0xbfb8aa3b, v45
	v_exp_f32_e32 v46, v46
	v_exp_f32_e32 v47, v47
	v_add_f32_e32 v46, 1.0, v46
	v_add_f32_e32 v47, 1.0, v47
	v_rcp_f32_e32 v46, v46
	v_rcp_f32_e32 v47, v47
	s_nop 0
	v_pk_mul_f32 v[44:45], v[44:45], v[46:47]
	s_nop 0
	v_pk_mul_f32 v[42:43], v[42:43], v[44:45]
	v_mul_f32_e32 v44, 0xbfb8aa3b, v36
	v_mul_f32_e32 v45, 0xbfb8aa3b, v37
	v_exp_f32_e32 v44, v44
	v_exp_f32_e32 v45, v45
	v_add_f32_e32 v44, 1.0, v44
	v_add_f32_e32 v45, 1.0, v45
	v_rcp_f32_e32 v44, v44
	v_rcp_f32_e32 v45, v45
	s_nop 0
	v_pk_mul_f32 v[36:37], v[36:37], v[44:45]
	s_nop 0
	v_pk_mul_f32 v[36:37], v[32:33], v[36:37]
	v_pk_fma_f32 v[32:33], v[74:75], v[218:219], v[38:39] op_sel:[0,1,0] neg_lo:[1,0,0] neg_hi:[1,0,0]
	s_nop 0
	v_pk_fma_f32 v[32:33], v[32:33], v[222:223], v[78:79] op_sel_hi:[1,0,1]
	s_nop 0
	v_mul_f32_e32 v38, 0xbfb8aa3b, v32
	v_mul_f32_e32 v39, 0xbfb8aa3b, v33
	v_exp_f32_e32 v38, v38
	v_exp_f32_e32 v39, v39
	v_add_f32_e32 v38, 1.0, v38
	v_add_f32_e32 v39, 1.0, v39
	v_rcp_f32_e32 v38, v38
	v_rcp_f32_e32 v39, v39
	s_nop 0
	v_pk_mul_f32 v[32:33], v[32:33], v[38:39]
	s_nop 0
	v_pk_mul_f32 v[38:39], v[34:35], v[32:33]
	v_cvt_pk_bf16_f32 v34, v36, v37
	v_mad_i64_i32 v[36:37], s[14:15], v208, s1, v[144:145]
	v_lshl_add_u64 v[36:37], v[36:37], 0, s[10:11]
	v_cvt_pk_bf16_f32 v32, v40, v41
	v_cvt_pk_bf16_f32 v33, v42, v43
	v_cvt_pk_bf16_f32 v35, v38, v39
	v_lshl_add_u64 v[36:37], v[36:37], 0, v[146:147]
	global_store_dwordx4 v[36:37], v[32:35], off
	s_nop 1
	v_mul_f32_e32 v32, 0xbfb8aa3b, v28
	v_mul_f32_e32 v33, 0xbfb8aa3b, v29
	v_exp_f32_e32 v32, v32
	v_exp_f32_e32 v33, v33
	v_add_f32_e32 v32, 1.0, v32
	v_add_f32_e32 v33, 1.0, v33
	v_rcp_f32_e32 v32, v32
	v_rcp_f32_e32 v33, v33
	s_nop 0
	v_pk_mul_f32 v[28:29], v[28:29], v[32:33]
	s_nop 0
	v_pk_mul_f32 v[24:25], v[24:25], v[28:29]
	v_pk_fma_f32 v[28:29], v[94:95], v[220:221], v[30:31] op_sel:[0,1,0] neg_lo:[1,0,0] neg_hi:[1,0,0]
	s_nop 0
	v_pk_fma_f32 v[28:29], v[28:29], v[224:225], v[98:99] op_sel_hi:[1,0,1]
	s_nop 0
	v_mul_f32_e32 v30, 0xbfb8aa3b, v28
	v_mul_f32_e32 v31, 0xbfb8aa3b, v29
	v_exp_f32_e32 v30, v30
	v_exp_f32_e32 v31, v31
	v_add_f32_e32 v30, 1.0, v30
	v_add_f32_e32 v31, 1.0, v31
	v_rcp_f32_e32 v30, v30
	v_rcp_f32_e32 v31, v31
	s_nop 0
	v_pk_mul_f32 v[28:29], v[28:29], v[30:31]
	s_nop 0
	v_pk_mul_f32 v[26:27], v[26:27], v[28:29]
	v_mul_f32_e32 v28, 0xbfb8aa3b, v20
	v_mul_f32_e32 v29, 0xbfb8aa3b, v21
	v_exp_f32_e32 v28, v28
	v_exp_f32_e32 v29, v29
	v_add_f32_e32 v28, 1.0, v28
	v_add_f32_e32 v29, 1.0, v29
	v_rcp_f32_e32 v28, v28
	v_rcp_f32_e32 v29, v29
	s_nop 0
	v_pk_mul_f32 v[20:21], v[20:21], v[28:29]
	s_nop 0
	v_pk_mul_f32 v[20:21], v[16:17], v[20:21]
	v_pk_fma_f32 v[16:17], v[74:75], v[220:221], v[22:23] op_sel:[0,1,0] neg_lo:[1,0,0] neg_hi:[1,0,0]
	s_nop 0
	v_pk_fma_f32 v[16:17], v[16:17], v[224:225], v[78:79] op_sel_hi:[1,0,1]
	s_nop 0
	v_mul_f32_e32 v22, 0xbfb8aa3b, v16
	v_mul_f32_e32 v23, 0xbfb8aa3b, v17
	v_exp_f32_e32 v22, v22
	v_exp_f32_e32 v23, v23
	v_add_f32_e32 v22, 1.0, v22
	v_add_f32_e32 v23, 1.0, v23
	v_rcp_f32_e32 v22, v22
	v_rcp_f32_e32 v23, v23
	s_nop 0
	v_pk_mul_f32 v[16:17], v[16:17], v[22:23]
	s_nop 0
	v_pk_mul_f32 v[22:23], v[18:19], v[16:17]
	v_cvt_pk_bf16_f32 v18, v20, v21
	v_mad_i64_i32 v[20:21], s[14:15], v212, s1, v[144:145]
	v_lshl_add_u64 v[20:21], v[20:21], 0, s[10:11]
	v_cvt_pk_bf16_f32 v16, v24, v25
	v_cvt_pk_bf16_f32 v17, v26, v27
	v_cvt_pk_bf16_f32 v19, v22, v23
	v_lshl_add_u64 v[20:21], v[20:21], 0, v[146:147]
	global_store_dwordx4 v[20:21], v[16:19], off
	s_nop 1
	v_mul_f32_e32 v16, 0xbfb8aa3b, v12
	v_mul_f32_e32 v17, 0xbfb8aa3b, v13
	v_exp_f32_e32 v16, v16
	v_exp_f32_e32 v17, v17
	v_add_f32_e32 v16, 1.0, v16
	v_add_f32_e32 v17, 1.0, v17
	v_rcp_f32_e32 v16, v16
	v_rcp_f32_e32 v17, v17
	s_nop 0
	v_pk_mul_f32 v[12:13], v[12:13], v[16:17]
	s_nop 0
	v_pk_mul_f32 v[8:9], v[8:9], v[12:13]
	v_pk_fma_f32 v[12:13], v[94:95], v[160:161], v[14:15] op_sel:[0,1,0] neg_lo:[1,0,0] neg_hi:[1,0,0]
	s_nop 0
	v_pk_fma_f32 v[12:13], v[12:13], v[162:163], v[98:99] op_sel_hi:[1,0,1]
	s_nop 0
	v_mul_f32_e32 v14, 0xbfb8aa3b, v12
	v_mul_f32_e32 v15, 0xbfb8aa3b, v13
	v_exp_f32_e32 v14, v14
	v_exp_f32_e32 v15, v15
	v_add_f32_e32 v14, 1.0, v14
	v_add_f32_e32 v15, 1.0, v15
	v_rcp_f32_e32 v14, v14
	v_rcp_f32_e32 v15, v15
	s_nop 0
	v_pk_mul_f32 v[12:13], v[12:13], v[14:15]
	s_nop 0
	v_pk_mul_f32 v[10:11], v[10:11], v[12:13]
	v_mul_f32_e32 v12, 0xbfb8aa3b, v4
	v_mul_f32_e32 v13, 0xbfb8aa3b, v5
	v_exp_f32_e32 v12, v12
	v_exp_f32_e32 v13, v13
	v_add_f32_e32 v12, 1.0, v12
	v_add_f32_e32 v13, 1.0, v13
	v_rcp_f32_e32 v12, v12
	v_rcp_f32_e32 v13, v13
	s_nop 0
	v_pk_mul_f32 v[4:5], v[4:5], v[12:13]
	s_nop 0
	v_pk_mul_f32 v[4:5], v[0:1], v[4:5]
	v_pk_fma_f32 v[0:1], v[74:75], v[160:161], v[6:7] op_sel:[0,1,0] neg_lo:[1,0,0] neg_hi:[1,0,0]
	s_nop 0
	v_pk_fma_f32 v[0:1], v[0:1], v[162:163], v[78:79] op_sel_hi:[1,0,1]
	s_nop 0
	v_mul_f32_e32 v6, 0xbfb8aa3b, v0
	v_mul_f32_e32 v7, 0xbfb8aa3b, v1
	v_exp_f32_e32 v6, v6
	v_exp_f32_e32 v7, v7
	v_add_f32_e32 v6, 1.0, v6
	v_add_f32_e32 v7, 1.0, v7
	v_rcp_f32_e32 v6, v6
	v_rcp_f32_e32 v7, v7
	s_nop 0
	v_pk_mul_f32 v[0:1], v[0:1], v[6:7]
	s_nop 0
	v_pk_mul_f32 v[6:7], v[2:3], v[0:1]
	v_cvt_pk_bf16_f32 v2, v4, v5
	v_mad_i64_i32 v[4:5], s[14:15], v206, s1, v[144:145]
	v_lshl_add_u64 v[4:5], v[4:5], 0, s[10:11]
	v_cvt_pk_bf16_f32 v0, v8, v9
	v_cvt_pk_bf16_f32 v1, v10, v11
	v_cvt_pk_bf16_f32 v3, v6, v7
	v_lshl_add_u64 v[4:5], v[4:5], 0, v[146:147]
	s_mov_b64 s[14:15], s[44:45]
	s_mov_b64 s[10:11], s[42:43]
	global_store_dwordx4 v[4:5], v[0:3], off
	s_cbranch_vccz .LBB0_875
	s_waitcnt vmcnt(0)
	s_cmpk_gt_u32 s18, 0xff
	s_cbranch_scc1 .LBB0_882
	s_barrier
